# GEMM1 epilogue stores (HM/HG outputs) marked nt so streamed outputs compete less with the re-read operand panels in cache
# baseline (speedup 1.0000x reference)
; __device__ __forceinline__ float siluf_(float x) { return x * sigmoidf_(x); }
;     __device__ __forceinline__ void operator()(f32x4 (&acc)[2][2][4][2], const Unit& u, int wr, int wc, int fr, int fq) const {
;     ...
;         const int row0 = u.pm * BM + wr * 64 + fr, col0 = colt + wc * 32 + 8 * fq;
; #pragma unroll
;         for (int ai = 0; ai < 2; ++ai)
; #pragma unroll
;             for (int m = 0; m < 4; ++m) { bf16_t* rowp = base + (size_t)(row0 + ai * HALF + m * 16) * ldc + col0;
; #pragma unroll
;                 for (int bj = 0; bj < 2; ++bj) { f32x4 v0 = acc[ai][bj][m][0] * scale, v1 = acc[ai][bj][m][1] * scale;
;                     if (act == 1) {
; #pragma unroll
;                         for (int j = 0; j < 4; ++j) { v0[j] = siluf_(v0[j]); v1[j] = siluf_(v1[j]); } }
;                     u32x4 w; w.x = pk2(v0[0], v0[1]); w.y = pk2(v0[2], v0[3]); w.z = pk2(v1[0], v1[1]); w.w = pk2(v1[2], v1[3]);
;                     *(u32x4*)(rowp + bj * HALF) = w; } }
.LBB0_266:
	s_mov_b32 s91, s90
	s_mov_b32 s88, s90
	s_mov_b32 s89, s90
	v_mad_i64_i32 v[154:155], s[70:71], v150, s50, v[152:153]
	v_cvt_pk_bf16_f32 v178, v158, v159
	v_cvt_pk_bf16_f32 v179, v156, v157
	v_cvt_pk_bf16_f32 v180, v162, v163
	v_cvt_pk_bf16_f32 v181, v160, v161
	v_pk_mul_f32 v[156:157], v[124:125], s[88:89]
	v_pk_mul_f32 v[158:159], v[122:123], s[90:91]
	v_pk_mul_f32 v[160:161], v[120:121], s[88:89]
	s_and_b64 vcc, exec, s[44:45]
	v_pk_mul_f32 v[162:163], v[118:119], s[90:91]
	global_store_dwordx4 v[154:155], v[178:181], off nt
	s_cbranch_vccnz .LBB0_268
	v_mul_f32_e32 v0, 0xbfb8aa3b, v158
	v_exp_f32_e32 v0, v0
	s_nop 0
	v_add_f32_e32 v0, 1.0, v0
	v_rcp_f32_e32 v178, v0
	v_mul_f32_e32 v0, 0xbfb8aa3b, v162
	v_exp_f32_e32 v0, v0
	s_nop 0
	v_add_f32_e32 v0, 1.0, v0
	v_rcp_f32_e32 v180, v0
	v_mul_f32_e32 v0, 0xbfb8aa3b, v159
	v_exp_f32_e32 v0, v0
	s_nop 0
	v_add_f32_e32 v0, 1.0, v0
	v_rcp_f32_e32 v179, v0
	v_mul_f32_e32 v0, 0xbfb8aa3b, v163
	v_exp_f32_e32 v0, v0
	v_pk_mul_f32 v[158:159], v[158:159], v[178:179]
	v_add_f32_e32 v0, 1.0, v0
	v_rcp_f32_e32 v181, v0
	v_mul_f32_e32 v0, 0xbfb8aa3b, v156
	v_exp_f32_e32 v0, v0
	v_pk_mul_f32 v[162:163], v[162:163], v[180:181]
	v_add_f32_e32 v0, 1.0, v0
	v_rcp_f32_e32 v182, v0
	v_mul_f32_e32 v0, 0xbfb8aa3b, v160
	v_exp_f32_e32 v0, v0
	s_nop 0
	v_add_f32_e32 v0, 1.0, v0
	v_rcp_f32_e32 v184, v0
	v_mul_f32_e32 v0, 0xbfb8aa3b, v157
	v_exp_f32_e32 v0, v0
	s_nop 0
	v_add_f32_e32 v0, 1.0, v0
	v_rcp_f32_e32 v183, v0
	v_mul_f32_e32 v0, 0xbfb8aa3b, v161
	v_exp_f32_e32 v0, v0
	v_pk_mul_f32 v[156:157], v[156:157], v[182:183]
	v_add_f32_e32 v0, 1.0, v0
	v_rcp_f32_e32 v185, v0
	s_nop 0
	v_pk_mul_f32 v[160:161], v[160:161], v[184:185]
.LBB0_268:
	s_nop 0
	v_cvt_pk_bf16_f32 v178, v158, v159
	v_cvt_pk_bf16_f32 v179, v156, v157
	v_cvt_pk_bf16_f32 v180, v162, v163
	v_cvt_pk_bf16_f32 v181, v160, v161
	v_pk_mul_f32 v[156:157], v[100:101], s[88:89]
	v_pk_mul_f32 v[158:159], v[98:99], s[90:91]
	v_pk_mul_f32 v[160:161], v[112:113], s[88:89]
	s_and_b64 vcc, exec, s[44:45]
	v_pk_mul_f32 v[162:163], v[110:111], s[90:91]
	global_store_dwordx4 v[154:155], v[178:181], off offset:256 nt
	s_cbranch_vccnz .LBB0_270
	v_mul_f32_e32 v0, 0xbfb8aa3b, v158
	v_exp_f32_e32 v0, v0
	s_nop 0
	v_add_f32_e32 v0, 1.0, v0
	v_rcp_f32_e32 v154, v0
	v_mul_f32_e32 v0, 0xbfb8aa3b, v162
	v_exp_f32_e32 v0, v0
	s_nop 0
	v_add_f32_e32 v0, 1.0, v0
	v_rcp_f32_e32 v178, v0
	v_mul_f32_e32 v0, 0xbfb8aa3b, v159
	v_exp_f32_e32 v0, v0
	s_nop 0
	v_add_f32_e32 v0, 1.0, v0
	v_rcp_f32_e32 v155, v0
	v_mul_f32_e32 v0, 0xbfb8aa3b, v163
	v_exp_f32_e32 v0, v0
	v_pk_mul_f32 v[158:159], v[158:159], v[154:155]
	v_add_f32_e32 v0, 1.0, v0
	v_rcp_f32_e32 v179, v0
	v_mul_f32_e32 v0, 0xbfb8aa3b, v156
	v_exp_f32_e32 v0, v0
	v_pk_mul_f32 v[162:163], v[162:163], v[178:179]
	v_add_f32_e32 v0, 1.0, v0
	v_rcp_f32_e32 v180, v0
	v_mul_f32_e32 v0, 0xbfb8aa3b, v160
	v_exp_f32_e32 v0, v0
	s_nop 0
	v_add_f32_e32 v0, 1.0, v0
	v_rcp_f32_e32 v182, v0
	v_mul_f32_e32 v0, 0xbfb8aa3b, v157
	v_exp_f32_e32 v0, v0
	s_nop 0
	v_add_f32_e32 v0, 1.0, v0
	v_rcp_f32_e32 v181, v0
	v_mul_f32_e32 v0, 0xbfb8aa3b, v161
	v_exp_f32_e32 v0, v0
	v_pk_mul_f32 v[156:157], v[156:157], v[180:181]
	v_add_f32_e32 v0, 1.0, v0
	v_rcp_f32_e32 v183, v0
	s_nop 0
	v_pk_mul_f32 v[160:161], v[160:161], v[182:183]
.LBB0_270:
	v_or_b32_e32 v0, 16, v150
	s_mov_b32 s88, s90
	s_mov_b32 s89, s90
	v_mad_i64_i32 v[154:155], s[70:71], v0, s50, v[152:153]
	v_cvt_pk_bf16_f32 v178, v158, v159
	v_cvt_pk_bf16_f32 v179, v156, v157
	v_cvt_pk_bf16_f32 v180, v162, v163
	v_cvt_pk_bf16_f32 v181, v160, v161
	v_pk_mul_f32 v[156:157], v[108:109], s[88:89]
	v_pk_mul_f32 v[158:159], v[106:107], s[90:91]
	v_pk_mul_f32 v[160:161], v[104:105], s[88:89]
	s_and_b64 vcc, exec, s[44:45]
	v_pk_mul_f32 v[162:163], v[102:103], s[90:91]
	global_store_dwordx4 v[154:155], v[178:181], off nt
	s_cbranch_vccnz .LBB0_272
	v_mul_f32_e32 v0, 0xbfb8aa3b, v158
	v_exp_f32_e32 v0, v0
	s_nop 0
	v_add_f32_e32 v0, 1.0, v0
	v_rcp_f32_e32 v178, v0
	v_mul_f32_e32 v0, 0xbfb8aa3b, v162
	v_exp_f32_e32 v0, v0
	s_nop 0
	v_add_f32_e32 v0, 1.0, v0
	v_rcp_f32_e32 v180, v0
	v_mul_f32_e32 v0, 0xbfb8aa3b, v159
	v_exp_f32_e32 v0, v0
	s_nop 0
	v_add_f32_e32 v0, 1.0, v0
	v_rcp_f32_e32 v179, v0
	v_mul_f32_e32 v0, 0xbfb8aa3b, v163
	v_exp_f32_e32 v0, v0
	v_pk_mul_f32 v[158:159], v[158:159], v[178:179]
	v_add_f32_e32 v0, 1.0, v0
	v_rcp_f32_e32 v181, v0
	v_mul_f32_e32 v0, 0xbfb8aa3b, v156
	v_exp_f32_e32 v0, v0
	v_pk_mul_f32 v[162:163], v[162:163], v[180:181]
	v_add_f32_e32 v0, 1.0, v0
	v_rcp_f32_e32 v182, v0
	v_mul_f32_e32 v0, 0xbfb8aa3b, v160
	v_exp_f32_e32 v0, v0
	s_nop 0
	v_add_f32_e32 v0, 1.0, v0
	v_rcp_f32_e32 v184, v0
	v_mul_f32_e32 v0, 0xbfb8aa3b, v157
	v_exp_f32_e32 v0, v0
	s_nop 0
	v_add_f32_e32 v0, 1.0, v0
	v_rcp_f32_e32 v183, v0
	v_mul_f32_e32 v0, 0xbfb8aa3b, v161
	v_exp_f32_e32 v0, v0
	v_pk_mul_f32 v[156:157], v[156:157], v[182:183]
	v_add_f32_e32 v0, 1.0, v0
	v_rcp_f32_e32 v185, v0
	s_nop 0
	v_pk_mul_f32 v[160:161], v[160:161], v[184:185]
; __device__ __forceinline__ float siluf_(float x) { return x * sigmoidf_(x); }
;     __device__ __forceinline__ void operator()(f32x4 (&acc)[2][2][4][2], const Unit& u, int wr, int wc, int fr, int fq) const {
;     ...
;         const int row0 = u.pm * BM + wr * 64 + fr, col0 = colt + wc * 32 + 8 * fq;
; #pragma unroll
;         for (int ai = 0; ai < 2; ++ai)
; #pragma unroll
;             for (int m = 0; m < 4; ++m) { bf16_t* rowp = base + (size_t)(row0 + ai * HALF + m * 16) * ldc + col0;
; #pragma unroll
;                 for (int bj = 0; bj < 2; ++bj) { f32x4 v0 = acc[ai][bj][m][0] * scale, v1 = acc[ai][bj][m][1] * scale;
;                     if (act == 1) {
; #pragma unroll
;                         for (int j = 0; j < 4; ++j) { v0[j] = siluf_(v0[j]); v1[j] = siluf_(v1[j]); } }
;                     u32x4 w; w.x = pk2(v0[0], v0[1]); w.y = pk2(v0[2], v0[3]); w.z = pk2(v1[0], v1[1]); w.w = pk2(v1[2], v1[3]);
;                     *(u32x4*)(rowp + bj * HALF) = w; } }
.LBB0_272:
	s_nop 0
	v_cvt_pk_bf16_f32 v178, v158, v159
	v_cvt_pk_bf16_f32 v179, v156, v157
	v_cvt_pk_bf16_f32 v180, v162, v163
	v_cvt_pk_bf16_f32 v181, v160, v161
	v_pk_mul_f32 v[156:157], v[84:85], s[88:89]
	v_pk_mul_f32 v[158:159], v[82:83], s[90:91]
	v_pk_mul_f32 v[160:161], v[96:97], s[88:89]
	s_and_b64 vcc, exec, s[44:45]
	v_pk_mul_f32 v[162:163], v[94:95], s[90:91]
	global_store_dwordx4 v[154:155], v[178:181], off offset:256 nt
	s_cbranch_vccnz .LBB0_274
	v_mul_f32_e32 v0, 0xbfb8aa3b, v158
	v_exp_f32_e32 v0, v0
	s_nop 0
	v_add_f32_e32 v0, 1.0, v0
	v_rcp_f32_e32 v154, v0
	v_mul_f32_e32 v0, 0xbfb8aa3b, v162
	v_exp_f32_e32 v0, v0
	s_nop 0
	v_add_f32_e32 v0, 1.0, v0
	v_rcp_f32_e32 v178, v0
	v_mul_f32_e32 v0, 0xbfb8aa3b, v159
	v_exp_f32_e32 v0, v0
	s_nop 0
	v_add_f32_e32 v0, 1.0, v0
	v_rcp_f32_e32 v155, v0
	v_mul_f32_e32 v0, 0xbfb8aa3b, v163
	v_exp_f32_e32 v0, v0
	v_pk_mul_f32 v[158:159], v[158:159], v[154:155]
	v_add_f32_e32 v0, 1.0, v0
	v_rcp_f32_e32 v179, v0
	v_mul_f32_e32 v0, 0xbfb8aa3b, v156
	v_exp_f32_e32 v0, v0
	v_pk_mul_f32 v[162:163], v[162:163], v[178:179]
	v_add_f32_e32 v0, 1.0, v0
	v_rcp_f32_e32 v180, v0
	v_mul_f32_e32 v0, 0xbfb8aa3b, v160
	v_exp_f32_e32 v0, v0
	s_nop 0
	v_add_f32_e32 v0, 1.0, v0
	v_rcp_f32_e32 v182, v0
	v_mul_f32_e32 v0, 0xbfb8aa3b, v157
	v_exp_f32_e32 v0, v0
	s_nop 0
	v_add_f32_e32 v0, 1.0, v0
	v_rcp_f32_e32 v181, v0
	v_mul_f32_e32 v0, 0xbfb8aa3b, v161
	v_exp_f32_e32 v0, v0
	v_pk_mul_f32 v[156:157], v[156:157], v[180:181]
	v_add_f32_e32 v0, 1.0, v0
	v_rcp_f32_e32 v183, v0
	s_nop 0
	v_pk_mul_f32 v[160:161], v[160:161], v[182:183]
.LBB0_274:
	v_or_b32_e32 v0, 32, v150
	s_mov_b32 s88, s90
	s_mov_b32 s89, s90
	v_mad_i64_i32 v[154:155], s[70:71], v0, s50, v[152:153]
	v_cvt_pk_bf16_f32 v178, v158, v159
	v_cvt_pk_bf16_f32 v179, v156, v157
	v_cvt_pk_bf16_f32 v180, v162, v163
	v_cvt_pk_bf16_f32 v181, v160, v161
	v_pk_mul_f32 v[156:157], v[92:93], s[88:89]
	v_pk_mul_f32 v[158:159], v[90:91], s[90:91]
	v_pk_mul_f32 v[160:161], v[88:89], s[88:89]
	s_and_b64 vcc, exec, s[44:45]
	v_pk_mul_f32 v[162:163], v[86:87], s[90:91]
	global_store_dwordx4 v[154:155], v[178:181], off nt
	s_cbranch_vccnz .LBB0_276
	v_mul_f32_e32 v0, 0xbfb8aa3b, v158
	v_exp_f32_e32 v0, v0
	s_nop 0
	v_add_f32_e32 v0, 1.0, v0
	v_rcp_f32_e32 v178, v0
	v_mul_f32_e32 v0, 0xbfb8aa3b, v162
	v_exp_f32_e32 v0, v0
	s_nop 0
	v_add_f32_e32 v0, 1.0, v0
	v_rcp_f32_e32 v180, v0
	v_mul_f32_e32 v0, 0xbfb8aa3b, v159
	v_exp_f32_e32 v0, v0
	s_nop 0
	v_add_f32_e32 v0, 1.0, v0
	v_rcp_f32_e32 v179, v0
	v_mul_f32_e32 v0, 0xbfb8aa3b, v163
	v_exp_f32_e32 v0, v0
	v_pk_mul_f32 v[158:159], v[158:159], v[178:179]
	v_add_f32_e32 v0, 1.0, v0
	v_rcp_f32_e32 v181, v0
	v_mul_f32_e32 v0, 0xbfb8aa3b, v156
	v_exp_f32_e32 v0, v0
	v_pk_mul_f32 v[162:163], v[162:163], v[180:181]
	v_add_f32_e32 v0, 1.0, v0
	v_rcp_f32_e32 v182, v0
	v_mul_f32_e32 v0, 0xbfb8aa3b, v160
	v_exp_f32_e32 v0, v0
	s_nop 0
	v_add_f32_e32 v0, 1.0, v0
	v_rcp_f32_e32 v184, v0
	v_mul_f32_e32 v0, 0xbfb8aa3b, v157
	v_exp_f32_e32 v0, v0
	s_nop 0
	v_add_f32_e32 v0, 1.0, v0
	v_rcp_f32_e32 v183, v0
	v_mul_f32_e32 v0, 0xbfb8aa3b, v161
	v_exp_f32_e32 v0, v0
	v_pk_mul_f32 v[156:157], v[156:157], v[182:183]
	v_add_f32_e32 v0, 1.0, v0
	v_rcp_f32_e32 v185, v0
	s_nop 0
	v_pk_mul_f32 v[160:161], v[160:161], v[184:185]
.LBB0_276:
	s_nop 0
	v_cvt_pk_bf16_f32 v178, v158, v159
	v_cvt_pk_bf16_f32 v179, v156, v157
	v_cvt_pk_bf16_f32 v180, v162, v163
	v_cvt_pk_bf16_f32 v181, v160, v161
	v_pk_mul_f32 v[156:157], v[68:69], s[88:89]
	v_pk_mul_f32 v[158:159], v[66:67], s[90:91]
	v_pk_mul_f32 v[160:161], v[80:81], s[88:89]
	s_and_b64 vcc, exec, s[44:45]
	v_pk_mul_f32 v[162:163], v[78:79], s[90:91]
	global_store_dwordx4 v[154:155], v[178:181], off offset:256 nt
	s_cbranch_vccnz .LBB0_278
	v_mul_f32_e32 v0, 0xbfb8aa3b, v158
	v_exp_f32_e32 v0, v0
	s_nop 0
	v_add_f32_e32 v0, 1.0, v0
	v_rcp_f32_e32 v154, v0
	v_mul_f32_e32 v0, 0xbfb8aa3b, v162
	v_exp_f32_e32 v0, v0
	s_nop 0
	v_add_f32_e32 v0, 1.0, v0
	v_rcp_f32_e32 v178, v0
	v_mul_f32_e32 v0, 0xbfb8aa3b, v159
	v_exp_f32_e32 v0, v0
	s_nop 0
	v_add_f32_e32 v0, 1.0, v0
	v_rcp_f32_e32 v155, v0
	v_mul_f32_e32 v0, 0xbfb8aa3b, v163
	v_exp_f32_e32 v0, v0
	v_pk_mul_f32 v[158:159], v[158:159], v[154:155]
	v_add_f32_e32 v0, 1.0, v0
	v_rcp_f32_e32 v179, v0
	v_mul_f32_e32 v0, 0xbfb8aa3b, v156
	v_exp_f32_e32 v0, v0
	v_pk_mul_f32 v[162:163], v[162:163], v[178:179]
	v_add_f32_e32 v0, 1.0, v0
	v_rcp_f32_e32 v180, v0
	v_mul_f32_e32 v0, 0xbfb8aa3b, v160
	v_exp_f32_e32 v0, v0
	s_nop 0
	v_add_f32_e32 v0, 1.0, v0
	v_rcp_f32_e32 v182, v0
	v_mul_f32_e32 v0, 0xbfb8aa3b, v157
	v_exp_f32_e32 v0, v0
	s_nop 0
	v_add_f32_e32 v0, 1.0, v0
	v_rcp_f32_e32 v181, v0
	v_mul_f32_e32 v0, 0xbfb8aa3b, v161
	v_exp_f32_e32 v0, v0
	v_pk_mul_f32 v[156:157], v[156:157], v[180:181]
	v_add_f32_e32 v0, 1.0, v0
	v_rcp_f32_e32 v183, v0
	s_nop 0
	v_pk_mul_f32 v[160:161], v[160:161], v[182:183]
; __device__ __forceinline__ float siluf_(float x) { return x * sigmoidf_(x); }
;     __device__ __forceinline__ void operator()(f32x4 (&acc)[2][2][4][2], const Unit& u, int wr, int wc, int fr, int fq) const {
;     ...
;         const int row0 = u.pm * BM + wr * 64 + fr, col0 = colt + wc * 32 + 8 * fq;
; #pragma unroll
;         for (int ai = 0; ai < 2; ++ai)
; #pragma unroll
;             for (int m = 0; m < 4; ++m) { bf16_t* rowp = base + (size_t)(row0 + ai * HALF + m * 16) * ldc + col0;
; #pragma unroll
;                 for (int bj = 0; bj < 2; ++bj) { f32x4 v0 = acc[ai][bj][m][0] * scale, v1 = acc[ai][bj][m][1] * scale;
;                     if (act == 1) {
; #pragma unroll
;                         for (int j = 0; j < 4; ++j) { v0[j] = siluf_(v0[j]); v1[j] = siluf_(v1[j]); } }
;                     u32x4 w; w.x = pk2(v0[0], v0[1]); w.y = pk2(v0[2], v0[3]); w.z = pk2(v1[0], v1[1]); w.w = pk2(v1[2], v1[3]);
;                     *(u32x4*)(rowp + bj * HALF) = w; } }
.LBB0_278:
	v_or_b32_e32 v0, 48, v150
	s_mov_b32 s88, s90
	s_mov_b32 s89, s90
	v_mad_i64_i32 v[154:155], s[70:71], v0, s50, v[152:153]
	v_cvt_pk_bf16_f32 v178, v158, v159
	v_cvt_pk_bf16_f32 v179, v156, v157
	v_cvt_pk_bf16_f32 v180, v162, v163
	v_cvt_pk_bf16_f32 v181, v160, v161
	v_pk_mul_f32 v[156:157], v[76:77], s[88:89]
	v_pk_mul_f32 v[158:159], v[74:75], s[90:91]
	v_pk_mul_f32 v[160:161], v[72:73], s[88:89]
	s_and_b64 vcc, exec, s[44:45]
	v_pk_mul_f32 v[162:163], v[70:71], s[90:91]
	global_store_dwordx4 v[154:155], v[178:181], off nt
	s_cbranch_vccnz .LBB0_280
	v_mul_f32_e32 v0, 0xbfb8aa3b, v158
	v_exp_f32_e32 v0, v0
	s_nop 0
	v_add_f32_e32 v0, 1.0, v0
	v_rcp_f32_e32 v178, v0
	v_mul_f32_e32 v0, 0xbfb8aa3b, v162
	v_exp_f32_e32 v0, v0
	s_nop 0
	v_add_f32_e32 v0, 1.0, v0
	v_rcp_f32_e32 v180, v0
	v_mul_f32_e32 v0, 0xbfb8aa3b, v159
	v_exp_f32_e32 v0, v0
	s_nop 0
	v_add_f32_e32 v0, 1.0, v0
	v_rcp_f32_e32 v179, v0
	v_mul_f32_e32 v0, 0xbfb8aa3b, v163
	v_exp_f32_e32 v0, v0
	v_pk_mul_f32 v[158:159], v[158:159], v[178:179]
	v_add_f32_e32 v0, 1.0, v0
	v_rcp_f32_e32 v181, v0
	v_mul_f32_e32 v0, 0xbfb8aa3b, v156
	v_exp_f32_e32 v0, v0
	v_pk_mul_f32 v[162:163], v[162:163], v[180:181]
	v_add_f32_e32 v0, 1.0, v0
	v_rcp_f32_e32 v182, v0
	v_mul_f32_e32 v0, 0xbfb8aa3b, v160
	v_exp_f32_e32 v0, v0
	s_nop 0
	v_add_f32_e32 v0, 1.0, v0
	v_rcp_f32_e32 v184, v0
	v_mul_f32_e32 v0, 0xbfb8aa3b, v157
	v_exp_f32_e32 v0, v0
	s_nop 0
	v_add_f32_e32 v0, 1.0, v0
	v_rcp_f32_e32 v183, v0
	v_mul_f32_e32 v0, 0xbfb8aa3b, v161
	v_exp_f32_e32 v0, v0
	v_pk_mul_f32 v[156:157], v[156:157], v[182:183]
	v_add_f32_e32 v0, 1.0, v0
	v_rcp_f32_e32 v185, v0
	s_nop 0
	v_pk_mul_f32 v[160:161], v[160:161], v[184:185]
.LBB0_280:
	s_nop 0
	v_cvt_pk_bf16_f32 v178, v158, v159
	v_cvt_pk_bf16_f32 v179, v156, v157
	v_cvt_pk_bf16_f32 v180, v162, v163
	v_cvt_pk_bf16_f32 v181, v160, v161
	v_pk_mul_f32 v[156:157], v[52:53], s[88:89]
	v_pk_mul_f32 v[158:159], v[50:51], s[90:91]
	v_pk_mul_f32 v[160:161], v[64:65], s[88:89]
	s_and_b64 vcc, exec, s[44:45]
	v_pk_mul_f32 v[162:163], v[62:63], s[90:91]
	global_store_dwordx4 v[154:155], v[178:181], off offset:256 nt
	s_cbranch_vccnz .LBB0_282
	v_mul_f32_e32 v0, 0xbfb8aa3b, v158
	v_exp_f32_e32 v0, v0
	s_nop 0
	v_add_f32_e32 v0, 1.0, v0
	v_rcp_f32_e32 v154, v0
	v_mul_f32_e32 v0, 0xbfb8aa3b, v162
	v_exp_f32_e32 v0, v0
	s_nop 0
	v_add_f32_e32 v0, 1.0, v0
	v_rcp_f32_e32 v178, v0
	v_mul_f32_e32 v0, 0xbfb8aa3b, v159
	v_exp_f32_e32 v0, v0
	s_nop 0
	v_add_f32_e32 v0, 1.0, v0
	v_rcp_f32_e32 v155, v0
	v_mul_f32_e32 v0, 0xbfb8aa3b, v163
	v_exp_f32_e32 v0, v0
	v_pk_mul_f32 v[158:159], v[158:159], v[154:155]
	v_add_f32_e32 v0, 1.0, v0
	v_rcp_f32_e32 v179, v0
	v_mul_f32_e32 v0, 0xbfb8aa3b, v156
	v_exp_f32_e32 v0, v0
	v_pk_mul_f32 v[162:163], v[162:163], v[178:179]
	v_add_f32_e32 v0, 1.0, v0
	v_rcp_f32_e32 v180, v0
	v_mul_f32_e32 v0, 0xbfb8aa3b, v160
	v_exp_f32_e32 v0, v0
	s_nop 0
	v_add_f32_e32 v0, 1.0, v0
	v_rcp_f32_e32 v182, v0
	v_mul_f32_e32 v0, 0xbfb8aa3b, v157
	v_exp_f32_e32 v0, v0
	s_nop 0
	v_add_f32_e32 v0, 1.0, v0
	v_rcp_f32_e32 v181, v0
	v_mul_f32_e32 v0, 0xbfb8aa3b, v161
	v_exp_f32_e32 v0, v0
	v_pk_mul_f32 v[156:157], v[156:157], v[180:181]
	v_add_f32_e32 v0, 1.0, v0
	v_rcp_f32_e32 v183, v0
	s_nop 0
	v_pk_mul_f32 v[160:161], v[160:161], v[182:183]
.LBB0_282:
	v_add_u32_e32 v0, 0x80, v150
	s_mov_b32 s88, s90
	s_mov_b32 s89, s90
	v_mad_i64_i32 v[154:155], s[70:71], v0, s50, v[152:153]
	v_cvt_pk_bf16_f32 v178, v158, v159
	v_cvt_pk_bf16_f32 v179, v156, v157
	v_cvt_pk_bf16_f32 v180, v162, v163
	v_cvt_pk_bf16_f32 v181, v160, v161
	v_pk_mul_f32 v[156:157], v[60:61], s[88:89]
	v_pk_mul_f32 v[158:159], v[58:59], s[90:91]
	v_pk_mul_f32 v[160:161], v[56:57], s[88:89]
	s_and_b64 vcc, exec, s[44:45]
	v_pk_mul_f32 v[162:163], v[54:55], s[90:91]
	global_store_dwordx4 v[154:155], v[178:181], off nt
	s_cbranch_vccnz .LBB0_284
	v_mul_f32_e32 v0, 0xbfb8aa3b, v158
	v_exp_f32_e32 v0, v0
	s_nop 0
	v_add_f32_e32 v0, 1.0, v0
	v_rcp_f32_e32 v178, v0
	v_mul_f32_e32 v0, 0xbfb8aa3b, v162
	v_exp_f32_e32 v0, v0
	s_nop 0
	v_add_f32_e32 v0, 1.0, v0
	v_rcp_f32_e32 v180, v0
	v_mul_f32_e32 v0, 0xbfb8aa3b, v159
	v_exp_f32_e32 v0, v0
	s_nop 0
	v_add_f32_e32 v0, 1.0, v0
	v_rcp_f32_e32 v179, v0
	v_mul_f32_e32 v0, 0xbfb8aa3b, v163
	v_exp_f32_e32 v0, v0
	v_pk_mul_f32 v[158:159], v[158:159], v[178:179]
	v_add_f32_e32 v0, 1.0, v0
	v_rcp_f32_e32 v181, v0
	v_mul_f32_e32 v0, 0xbfb8aa3b, v156
	v_exp_f32_e32 v0, v0
	v_pk_mul_f32 v[162:163], v[162:163], v[180:181]
	v_add_f32_e32 v0, 1.0, v0
	v_rcp_f32_e32 v182, v0
	v_mul_f32_e32 v0, 0xbfb8aa3b, v160
	v_exp_f32_e32 v0, v0
	s_nop 0
	v_add_f32_e32 v0, 1.0, v0
	v_rcp_f32_e32 v184, v0
	v_mul_f32_e32 v0, 0xbfb8aa3b, v157
	v_exp_f32_e32 v0, v0
	s_nop 0
	v_add_f32_e32 v0, 1.0, v0
	v_rcp_f32_e32 v183, v0
	v_mul_f32_e32 v0, 0xbfb8aa3b, v161
	v_exp_f32_e32 v0, v0
	v_pk_mul_f32 v[156:157], v[156:157], v[182:183]
	v_add_f32_e32 v0, 1.0, v0
	v_rcp_f32_e32 v185, v0
	s_nop 0
	v_pk_mul_f32 v[160:161], v[160:161], v[184:185]
; __device__ __forceinline__ float siluf_(float x) { return x * sigmoidf_(x); }
;     __device__ __forceinline__ void operator()(f32x4 (&acc)[2][2][4][2], const Unit& u, int wr, int wc, int fr, int fq) const {
;     ...
;         const int row0 = u.pm * BM + wr * 64 + fr, col0 = colt + wc * 32 + 8 * fq;
; #pragma unroll
;         for (int ai = 0; ai < 2; ++ai)
; #pragma unroll
;             for (int m = 0; m < 4; ++m) { bf16_t* rowp = base + (size_t)(row0 + ai * HALF + m * 16) * ldc + col0;
; #pragma unroll
;                 for (int bj = 0; bj < 2; ++bj) { f32x4 v0 = acc[ai][bj][m][0] * scale, v1 = acc[ai][bj][m][1] * scale;
;                     if (act == 1) {
; #pragma unroll
;                         for (int j = 0; j < 4; ++j) { v0[j] = siluf_(v0[j]); v1[j] = siluf_(v1[j]); } }
;                     u32x4 w; w.x = pk2(v0[0], v0[1]); w.y = pk2(v0[2], v0[3]); w.z = pk2(v1[0], v1[1]); w.w = pk2(v1[2], v1[3]);
;                     *(u32x4*)(rowp + bj * HALF) = w; } }
.LBB0_284:
	s_nop 0
	v_cvt_pk_bf16_f32 v178, v158, v159
	v_cvt_pk_bf16_f32 v179, v156, v157
	v_cvt_pk_bf16_f32 v180, v162, v163
	v_cvt_pk_bf16_f32 v181, v160, v161
	v_pk_mul_f32 v[156:157], v[36:37], s[88:89]
	v_pk_mul_f32 v[158:159], v[34:35], s[90:91]
	v_pk_mul_f32 v[160:161], v[48:49], s[88:89]
	s_and_b64 vcc, exec, s[44:45]
	v_pk_mul_f32 v[162:163], v[46:47], s[90:91]
	global_store_dwordx4 v[154:155], v[178:181], off offset:256 nt
	s_cbranch_vccnz .LBB0_286
	v_mul_f32_e32 v0, 0xbfb8aa3b, v158
	v_exp_f32_e32 v0, v0
	s_nop 0
	v_add_f32_e32 v0, 1.0, v0
	v_rcp_f32_e32 v154, v0
	v_mul_f32_e32 v0, 0xbfb8aa3b, v162
	v_exp_f32_e32 v0, v0
	s_nop 0
	v_add_f32_e32 v0, 1.0, v0
	v_rcp_f32_e32 v178, v0
	v_mul_f32_e32 v0, 0xbfb8aa3b, v159
	v_exp_f32_e32 v0, v0
	s_nop 0
	v_add_f32_e32 v0, 1.0, v0
	v_rcp_f32_e32 v155, v0
	v_mul_f32_e32 v0, 0xbfb8aa3b, v163
	v_exp_f32_e32 v0, v0
	v_pk_mul_f32 v[158:159], v[158:159], v[154:155]
	v_add_f32_e32 v0, 1.0, v0
	v_rcp_f32_e32 v179, v0
	v_mul_f32_e32 v0, 0xbfb8aa3b, v156
	v_exp_f32_e32 v0, v0
	v_pk_mul_f32 v[162:163], v[162:163], v[178:179]
	v_add_f32_e32 v0, 1.0, v0
	v_rcp_f32_e32 v180, v0
	v_mul_f32_e32 v0, 0xbfb8aa3b, v160
	v_exp_f32_e32 v0, v0
	s_nop 0
	v_add_f32_e32 v0, 1.0, v0
	v_rcp_f32_e32 v182, v0
	v_mul_f32_e32 v0, 0xbfb8aa3b, v157
	v_exp_f32_e32 v0, v0
	s_nop 0
	v_add_f32_e32 v0, 1.0, v0
	v_rcp_f32_e32 v181, v0
	v_mul_f32_e32 v0, 0xbfb8aa3b, v161
	v_exp_f32_e32 v0, v0
	v_pk_mul_f32 v[156:157], v[156:157], v[180:181]
	v_add_f32_e32 v0, 1.0, v0
	v_rcp_f32_e32 v183, v0
	s_nop 0
	v_pk_mul_f32 v[160:161], v[160:161], v[182:183]
.LBB0_286:
	v_add_u32_e32 v0, 0x90, v150
	s_mov_b32 s88, s90
	s_mov_b32 s89, s90
	v_mad_i64_i32 v[154:155], s[70:71], v0, s50, v[152:153]
	v_cvt_pk_bf16_f32 v178, v158, v159
	v_cvt_pk_bf16_f32 v179, v156, v157
	v_cvt_pk_bf16_f32 v180, v162, v163
	v_cvt_pk_bf16_f32 v181, v160, v161
	v_pk_mul_f32 v[156:157], v[44:45], s[88:89]
	v_pk_mul_f32 v[158:159], v[42:43], s[90:91]
	v_pk_mul_f32 v[160:161], v[40:41], s[88:89]
	s_and_b64 vcc, exec, s[44:45]
	v_pk_mul_f32 v[162:163], v[38:39], s[90:91]
	global_store_dwordx4 v[154:155], v[178:181], off nt
	s_cbranch_vccnz .LBB0_288
	v_mul_f32_e32 v0, 0xbfb8aa3b, v158
	v_exp_f32_e32 v0, v0
	s_nop 0
	v_add_f32_e32 v0, 1.0, v0
	v_rcp_f32_e32 v178, v0
	v_mul_f32_e32 v0, 0xbfb8aa3b, v162
	v_exp_f32_e32 v0, v0
	s_nop 0
	v_add_f32_e32 v0, 1.0, v0
	v_rcp_f32_e32 v180, v0
	v_mul_f32_e32 v0, 0xbfb8aa3b, v159
	v_exp_f32_e32 v0, v0
	s_nop 0
	v_add_f32_e32 v0, 1.0, v0
	v_rcp_f32_e32 v179, v0
	v_mul_f32_e32 v0, 0xbfb8aa3b, v163
	v_exp_f32_e32 v0, v0
	v_pk_mul_f32 v[158:159], v[158:159], v[178:179]
	v_add_f32_e32 v0, 1.0, v0
	v_rcp_f32_e32 v181, v0
	v_mul_f32_e32 v0, 0xbfb8aa3b, v156
	v_exp_f32_e32 v0, v0
	v_pk_mul_f32 v[162:163], v[162:163], v[180:181]
	v_add_f32_e32 v0, 1.0, v0
	v_rcp_f32_e32 v182, v0
	v_mul_f32_e32 v0, 0xbfb8aa3b, v160
	v_exp_f32_e32 v0, v0
	s_nop 0
	v_add_f32_e32 v0, 1.0, v0
	v_rcp_f32_e32 v184, v0
	v_mul_f32_e32 v0, 0xbfb8aa3b, v157
	v_exp_f32_e32 v0, v0
	s_nop 0
	v_add_f32_e32 v0, 1.0, v0
	v_rcp_f32_e32 v183, v0
	v_mul_f32_e32 v0, 0xbfb8aa3b, v161
	v_exp_f32_e32 v0, v0
	v_pk_mul_f32 v[156:157], v[156:157], v[182:183]
	v_add_f32_e32 v0, 1.0, v0
	v_rcp_f32_e32 v185, v0
	s_nop 0
	v_pk_mul_f32 v[160:161], v[160:161], v[184:185]
.LBB0_288:
	s_nop 0
	v_cvt_pk_bf16_f32 v178, v158, v159
	v_cvt_pk_bf16_f32 v179, v156, v157
	v_cvt_pk_bf16_f32 v180, v162, v163
	v_cvt_pk_bf16_f32 v181, v160, v161
	v_pk_mul_f32 v[156:157], v[20:21], s[88:89]
	v_pk_mul_f32 v[158:159], v[18:19], s[90:91]
	v_pk_mul_f32 v[160:161], v[32:33], s[88:89]
	s_and_b64 vcc, exec, s[44:45]
	v_pk_mul_f32 v[162:163], v[30:31], s[90:91]
	global_store_dwordx4 v[154:155], v[178:181], off offset:256 nt
	s_cbranch_vccnz .LBB0_290
	v_mul_f32_e32 v0, 0xbfb8aa3b, v158
	v_exp_f32_e32 v0, v0
	s_nop 0
	v_add_f32_e32 v0, 1.0, v0
	v_rcp_f32_e32 v154, v0
	v_mul_f32_e32 v0, 0xbfb8aa3b, v162
	v_exp_f32_e32 v0, v0
	s_nop 0
	v_add_f32_e32 v0, 1.0, v0
	v_rcp_f32_e32 v178, v0
	v_mul_f32_e32 v0, 0xbfb8aa3b, v159
	v_exp_f32_e32 v0, v0
	s_nop 0
	v_add_f32_e32 v0, 1.0, v0
	v_rcp_f32_e32 v155, v0
	v_mul_f32_e32 v0, 0xbfb8aa3b, v163
	v_exp_f32_e32 v0, v0
	v_pk_mul_f32 v[158:159], v[158:159], v[154:155]
	v_add_f32_e32 v0, 1.0, v0
	v_rcp_f32_e32 v179, v0
	v_mul_f32_e32 v0, 0xbfb8aa3b, v156
	v_exp_f32_e32 v0, v0
	v_pk_mul_f32 v[162:163], v[162:163], v[178:179]
	v_add_f32_e32 v0, 1.0, v0
	v_rcp_f32_e32 v180, v0
	v_mul_f32_e32 v0, 0xbfb8aa3b, v160
	v_exp_f32_e32 v0, v0
	s_nop 0
	v_add_f32_e32 v0, 1.0, v0
	v_rcp_f32_e32 v182, v0
	v_mul_f32_e32 v0, 0xbfb8aa3b, v157
	v_exp_f32_e32 v0, v0
	s_nop 0
	v_add_f32_e32 v0, 1.0, v0
	v_rcp_f32_e32 v181, v0
	v_mul_f32_e32 v0, 0xbfb8aa3b, v161
	v_exp_f32_e32 v0, v0
	v_pk_mul_f32 v[156:157], v[156:157], v[180:181]
	v_add_f32_e32 v0, 1.0, v0
	v_rcp_f32_e32 v183, v0
	s_nop 0
	v_pk_mul_f32 v[160:161], v[160:161], v[182:183]
; __device__ __forceinline__ float siluf_(float x) { return x * sigmoidf_(x); }
;     __device__ __forceinline__ void operator()(f32x4 (&acc)[2][2][4][2], const Unit& u, int wr, int wc, int fr, int fq) const {
;     ...
;         const int row0 = u.pm * BM + wr * 64 + fr, col0 = colt + wc * 32 + 8 * fq;
; #pragma unroll
;         for (int ai = 0; ai < 2; ++ai)
; #pragma unroll
;             for (int m = 0; m < 4; ++m) { bf16_t* rowp = base + (size_t)(row0 + ai * HALF + m * 16) * ldc + col0;
; #pragma unroll
;                 for (int bj = 0; bj < 2; ++bj) { f32x4 v0 = acc[ai][bj][m][0] * scale, v1 = acc[ai][bj][m][1] * scale;
;                     if (act == 1) {
; #pragma unroll
;                         for (int j = 0; j < 4; ++j) { v0[j] = siluf_(v0[j]); v1[j] = siluf_(v1[j]); } }
;                     u32x4 w; w.x = pk2(v0[0], v0[1]); w.y = pk2(v0[2], v0[3]); w.z = pk2(v1[0], v1[1]); w.w = pk2(v1[2], v1[3]);
;                     *(u32x4*)(rowp + bj * HALF) = w; } }
.LBB0_290:
	v_add_u32_e32 v0, 0xa0, v150
	s_mov_b32 s88, s90
	s_mov_b32 s89, s90
	v_mad_i64_i32 v[154:155], s[70:71], v0, s50, v[152:153]
	v_cvt_pk_bf16_f32 v178, v158, v159
	v_cvt_pk_bf16_f32 v179, v156, v157
	v_cvt_pk_bf16_f32 v180, v162, v163
	v_cvt_pk_bf16_f32 v181, v160, v161
	v_pk_mul_f32 v[156:157], v[28:29], s[88:89]
	v_pk_mul_f32 v[158:159], v[26:27], s[90:91]
	v_pk_mul_f32 v[160:161], v[24:25], s[88:89]
	s_and_b64 vcc, exec, s[44:45]
	v_pk_mul_f32 v[162:163], v[22:23], s[90:91]
	global_store_dwordx4 v[154:155], v[178:181], off nt
	s_cbranch_vccnz .LBB0_292
	v_mul_f32_e32 v0, 0xbfb8aa3b, v158
	v_exp_f32_e32 v0, v0
	s_nop 0
	v_add_f32_e32 v0, 1.0, v0
	v_rcp_f32_e32 v178, v0
	v_mul_f32_e32 v0, 0xbfb8aa3b, v162
	v_exp_f32_e32 v0, v0
	s_nop 0
	v_add_f32_e32 v0, 1.0, v0
	v_rcp_f32_e32 v180, v0
	v_mul_f32_e32 v0, 0xbfb8aa3b, v159
	v_exp_f32_e32 v0, v0
	s_nop 0
	v_add_f32_e32 v0, 1.0, v0
	v_rcp_f32_e32 v179, v0
	v_mul_f32_e32 v0, 0xbfb8aa3b, v163
	v_exp_f32_e32 v0, v0
	v_pk_mul_f32 v[158:159], v[158:159], v[178:179]
	v_add_f32_e32 v0, 1.0, v0
	v_rcp_f32_e32 v181, v0
	v_mul_f32_e32 v0, 0xbfb8aa3b, v156
	v_exp_f32_e32 v0, v0
	v_pk_mul_f32 v[162:163], v[162:163], v[180:181]
	v_add_f32_e32 v0, 1.0, v0
	v_rcp_f32_e32 v182, v0
	v_mul_f32_e32 v0, 0xbfb8aa3b, v160
	v_exp_f32_e32 v0, v0
	s_nop 0
	v_add_f32_e32 v0, 1.0, v0
	v_rcp_f32_e32 v184, v0
	v_mul_f32_e32 v0, 0xbfb8aa3b, v157
	v_exp_f32_e32 v0, v0
	s_nop 0
	v_add_f32_e32 v0, 1.0, v0
	v_rcp_f32_e32 v183, v0
	v_mul_f32_e32 v0, 0xbfb8aa3b, v161
	v_exp_f32_e32 v0, v0
	v_pk_mul_f32 v[156:157], v[156:157], v[182:183]
	v_add_f32_e32 v0, 1.0, v0
	v_rcp_f32_e32 v185, v0
	s_nop 0
	v_pk_mul_f32 v[160:161], v[160:161], v[184:185]
.LBB0_292:
	s_nop 0
	v_cvt_pk_bf16_f32 v178, v158, v159
	v_cvt_pk_bf16_f32 v179, v156, v157
	v_cvt_pk_bf16_f32 v180, v162, v163
	v_cvt_pk_bf16_f32 v181, v160, v161
	v_pk_mul_f32 v[156:157], v[4:5], s[88:89]
	v_pk_mul_f32 v[158:159], v[2:3], s[90:91]
	v_pk_mul_f32 v[160:161], v[16:17], s[88:89]
	s_and_b64 vcc, exec, s[44:45]
	v_pk_mul_f32 v[162:163], v[14:15], s[90:91]
	global_store_dwordx4 v[154:155], v[178:181], off offset:256 nt
	s_cbranch_vccnz .LBB0_294
	v_mul_f32_e32 v0, 0xbfb8aa3b, v158
	v_exp_f32_e32 v0, v0
	s_nop 0
	v_add_f32_e32 v0, 1.0, v0
	v_rcp_f32_e32 v154, v0
	v_mul_f32_e32 v0, 0xbfb8aa3b, v162
	v_exp_f32_e32 v0, v0
	s_nop 0
	v_add_f32_e32 v0, 1.0, v0
	v_rcp_f32_e32 v178, v0
	v_mul_f32_e32 v0, 0xbfb8aa3b, v159
	v_exp_f32_e32 v0, v0
	s_nop 0
	v_add_f32_e32 v0, 1.0, v0
	v_rcp_f32_e32 v155, v0
	v_mul_f32_e32 v0, 0xbfb8aa3b, v163
	v_exp_f32_e32 v0, v0
	v_pk_mul_f32 v[158:159], v[158:159], v[154:155]
	v_add_f32_e32 v0, 1.0, v0
	v_rcp_f32_e32 v179, v0
	v_mul_f32_e32 v0, 0xbfb8aa3b, v156
	v_exp_f32_e32 v0, v0
	v_pk_mul_f32 v[162:163], v[162:163], v[178:179]
	v_add_f32_e32 v0, 1.0, v0
	v_rcp_f32_e32 v180, v0
	v_mul_f32_e32 v0, 0xbfb8aa3b, v160
	v_exp_f32_e32 v0, v0
	s_nop 0
	v_add_f32_e32 v0, 1.0, v0
	v_rcp_f32_e32 v182, v0
	v_mul_f32_e32 v0, 0xbfb8aa3b, v157
	v_exp_f32_e32 v0, v0
	s_nop 0
	v_add_f32_e32 v0, 1.0, v0
	v_rcp_f32_e32 v181, v0
	v_mul_f32_e32 v0, 0xbfb8aa3b, v161
	v_exp_f32_e32 v0, v0
	v_pk_mul_f32 v[156:157], v[156:157], v[180:181]
	v_add_f32_e32 v0, 1.0, v0
	v_rcp_f32_e32 v183, v0
	s_nop 0
	v_pk_mul_f32 v[160:161], v[160:161], v[182:183]
.LBB0_294:
	v_add_u32_e32 v0, 0xb0, v150
	v_mad_i64_i32 v[154:155], s[70:71], v0, s50, v[152:153]
	s_mov_b32 s70, s90
	s_mov_b32 s71, s90
	v_cvt_pk_bf16_f32 v178, v158, v159
	v_cvt_pk_bf16_f32 v179, v156, v157
	v_cvt_pk_bf16_f32 v180, v162, v163
	v_cvt_pk_bf16_f32 v181, v160, v161
	v_pk_mul_f32 v[156:157], v[12:13], s[70:71]
	v_pk_mul_f32 v[158:159], v[10:11], s[90:91]
	v_pk_mul_f32 v[160:161], v[8:9], s[70:71]
	s_and_b64 vcc, exec, s[44:45]
	v_pk_mul_f32 v[162:163], v[6:7], s[90:91]
	global_store_dwordx4 v[154:155], v[178:181], off nt
	s_cbranch_vccnz .LBB0_296
	v_mul_f32_e32 v0, 0xbfb8aa3b, v158
	v_exp_f32_e32 v0, v0
	s_nop 0
	v_add_f32_e32 v0, 1.0, v0
	v_rcp_f32_e32 v178, v0
	v_mul_f32_e32 v0, 0xbfb8aa3b, v162
	v_exp_f32_e32 v0, v0
	s_nop 0
	v_add_f32_e32 v0, 1.0, v0
	v_rcp_f32_e32 v180, v0
	v_mul_f32_e32 v0, 0xbfb8aa3b, v159
	v_exp_f32_e32 v0, v0
	s_nop 0
	v_add_f32_e32 v0, 1.0, v0
	v_rcp_f32_e32 v179, v0
	v_mul_f32_e32 v0, 0xbfb8aa3b, v163
	v_exp_f32_e32 v0, v0
	v_pk_mul_f32 v[158:159], v[158:159], v[178:179]
	v_add_f32_e32 v0, 1.0, v0
	v_rcp_f32_e32 v181, v0
	v_mul_f32_e32 v0, 0xbfb8aa3b, v156
	v_exp_f32_e32 v0, v0
	v_pk_mul_f32 v[162:163], v[162:163], v[180:181]
	v_add_f32_e32 v0, 1.0, v0
	v_rcp_f32_e32 v182, v0
	v_mul_f32_e32 v0, 0xbfb8aa3b, v160
	v_exp_f32_e32 v0, v0
	s_nop 0
	v_add_f32_e32 v0, 1.0, v0
	v_rcp_f32_e32 v184, v0
	v_mul_f32_e32 v0, 0xbfb8aa3b, v157
	v_exp_f32_e32 v0, v0
	s_nop 0
	v_add_f32_e32 v0, 1.0, v0
	v_rcp_f32_e32 v183, v0
	v_mul_f32_e32 v0, 0xbfb8aa3b, v161
	v_exp_f32_e32 v0, v0
	v_pk_mul_f32 v[156:157], v[156:157], v[182:183]
	v_add_f32_e32 v0, 1.0, v0
	v_rcp_f32_e32 v185, v0
	s_nop 0
	v_pk_mul_f32 v[160:161], v[160:161], v[184:185]
.LBB0_296:
	s_nop 0
	v_cvt_pk_bf16_f32 v178, v158, v159
	v_cvt_pk_bf16_f32 v179, v156, v157
	v_cvt_pk_bf16_f32 v180, v162, v163
	v_cvt_pk_bf16_f32 v181, v160, v161
	global_store_dwordx4 v[154:155], v[178:181], off offset:256 nt
	s_mov_b64 s[44:45], 0
; __device__ __forceinline__ float sigmoidf_(float x) { return __builtin_amdgcn_rcpf(1.0f + __expf(-x)); }
;     __device__ __forceinline__ void operator()(f32x4 (&acc)[2][2][4][2], const Unit& u, int wr, int wc, int fr, int fq) const {
;     ...
;         if (act >= 3) {
;             const int row0 = u.pm * BM + wr * 64 + fr, col0 = colt + wc * 32 + 8 * fq;
; #pragma unroll
;             for (int ai = 0; ai < 2; ++ai)
; #pragma unroll
;                 for (int m = 0; m < 4; ++m) { bf16_t* rowp = base + (size_t)(row0 + ai * HALF + m * 16) * ldc + col0;
;                     f32x4 v0 = acc[ai][0][m][0], v1 = acc[ai][0][m][1]; const f32x4 g0 = acc[ai][1][m][0], g1 = acc[ai][1][m][1];
; #pragma unroll
;                     for (int j = 0; j < 4; ++j) { const float s0 = sigmoidf_(g0[j]), s1 = sigmoidf_(g1[j]);
;                         v0[j] *= (act == 3) ? g0[j] * s0 : s0; v1[j] *= (act == 3) ? g1[j] * s1 : s1; }
;                     u32x4 w; w.x = pk2(v0[0], v0[1]); w.y = pk2(v0[2], v0[3]); w.z = pk2(v1[0], v1[1]); w.w = pk2(v1[2], v1[3]);
;                     *(u32x4*)rowp = w; }
;             return;
.LBB0_297:
	s_and_b64 vcc, exec, s[44:45]
	s_cbranch_vccz .LBB0_299
	v_mul_f32_e32 v0, 0xbfb8aa3b, v122
	v_exp_f32_e32 v0, v0
	v_mul_f32_e32 v151, 0xbfb8aa3b, v118
	v_exp_f32_e32 v151, v151
	v_mul_f32_e32 v154, 0xbfb8aa3b, v123
	v_add_f32_e32 v0, 1.0, v0
	v_rcp_f32_e32 v0, v0
	v_exp_f32_e32 v154, v154
	v_add_f32_e32 v151, 1.0, v151
	v_rcp_f32_e32 v151, v151
	v_mul_f32_e32 v155, v122, v0
	v_cndmask_b32_e64 v0, v0, v155, s[42:43]
	v_mul_f32_e32 v155, 0xbfb8aa3b, v119
	v_exp_f32_e32 v155, v155
	v_add_f32_e32 v154, 1.0, v154
	v_rcp_f32_e32 v154, v154
	v_mul_f32_e32 v156, v118, v151
	v_add_f32_e32 v155, 1.0, v155
	v_rcp_f32_e32 v155, v155
	v_cndmask_b32_e64 v151, v151, v156, s[42:43]
	v_mul_f32_e32 v156, v123, v154
	v_cndmask_b32_e64 v154, v154, v156, s[42:43]
	v_mul_f32_e32 v156, v119, v155
	v_mul_f32_e32 v157, 0xbfb8aa3b, v124
	v_exp_f32_e32 v157, v157
	v_cndmask_b32_e64 v155, v155, v156, s[42:43]
	v_mul_f32_e32 v156, 0xbfb8aa3b, v120
	v_exp_f32_e32 v156, v156
	v_add_f32_e32 v157, 1.0, v157
	v_rcp_f32_e32 v157, v157
	v_mul_f32_e32 v160, v127, v155
	v_add_f32_e32 v155, 1.0, v156
	v_rcp_f32_e32 v155, v155
	v_mul_f32_e32 v156, v124, v157
	v_cndmask_b32_e64 v156, v157, v156, s[42:43]
	v_mul_f32_e32 v158, 0xbfb8aa3b, v125
	v_mul_f32_e32 v157, v120, v155
	v_exp_f32_e32 v158, v158
	v_cndmask_b32_e64 v155, v155, v157, s[42:43]
	v_mul_f32_e32 v157, 0xbfb8aa3b, v121
	v_exp_f32_e32 v157, v157
	v_add_f32_e32 v158, 1.0, v158
	v_rcp_f32_e32 v158, v158
	v_mul_f32_e32 v161, v128, v155
	v_add_f32_e32 v155, 1.0, v157
	v_rcp_f32_e32 v155, v155
	v_mul_f32_e32 v157, v125, v158
	v_mul_f32_e32 v0, v114, v0
	v_mul_f32_e32 v154, v115, v154
	v_cndmask_b32_e64 v157, v158, v157, s[42:43]
	v_mul_f32_e32 v158, v121, v155
	v_mul_f32_e32 v151, v126, v151
	v_mul_f32_e32 v156, v116, v156
	v_mul_f32_e32 v157, v117, v157
	v_cndmask_b32_e64 v155, v155, v158, s[42:43]
	v_cvt_pk_bf16_f32 v154, v0, v154
	v_mul_f32_e32 v0, 0xbfb8aa3b, v106
	v_mul_f32_e32 v162, v129, v155
	v_cvt_pk_bf16_f32 v155, v156, v157
	v_cvt_pk_bf16_f32 v156, v151, v160
	v_exp_f32_e32 v0, v0
	v_mul_f32_e32 v151, 0xbfb8aa3b, v102
	v_exp_f32_e32 v151, v151
	v_mad_i64_i32 v[158:159], s[44:45], v150, s50, v[152:153]
	v_add_f32_e32 v0, 1.0, v0
	v_rcp_f32_e32 v0, v0
	v_add_f32_e32 v151, 1.0, v151
	v_rcp_f32_e32 v151, v151
	v_cvt_pk_bf16_f32 v157, v161, v162
	global_store_dwordx4 v[158:159], v[154:157], off nt
	v_mul_f32_e32 v158, 0xbfb8aa3b, v108
	v_exp_f32_e32 v158, v158
	v_mul_f32_e32 v155, v106, v0
	v_cndmask_b32_e64 v0, v0, v155, s[42:43]
	v_mul_f32_e32 v155, v102, v151
	v_mul_f32_e32 v156, 0xbfb8aa3b, v107
	v_exp_f32_e32 v156, v156
	v_cndmask_b32_e64 v151, v151, v155, s[42:43]
	v_mul_f32_e32 v155, 0xbfb8aa3b, v103
	v_exp_f32_e32 v155, v155
	v_add_f32_e32 v156, 1.0, v156
	v_rcp_f32_e32 v156, v156
	v_add_f32_e32 v158, 1.0, v158
	v_add_f32_e32 v155, 1.0, v155
	v_rcp_f32_e32 v155, v155
	v_mul_f32_e32 v157, v107, v156
	v_cndmask_b32_e64 v156, v156, v157, s[42:43]
	v_rcp_f32_e32 v158, v158
	v_mul_f32_e32 v157, v103, v155
	v_cndmask_b32_e64 v155, v155, v157, s[42:43]
	v_mul_f32_e32 v157, 0xbfb8aa3b, v104
	v_exp_f32_e32 v157, v157
	v_mul_f32_e32 v160, v111, v155
	v_mul_f32_e32 v159, 0xbfb8aa3b, v109
	v_exp_f32_e32 v159, v159
	v_add_f32_e32 v155, 1.0, v157
	v_rcp_f32_e32 v155, v155
	v_mul_f32_e32 v157, v108, v158
	v_cndmask_b32_e64 v157, v158, v157, s[42:43]
	v_add_f32_e32 v159, 1.0, v159
	v_mul_f32_e32 v158, v104, v155
	v_cndmask_b32_e64 v155, v155, v158, s[42:43]
	v_mul_f32_e32 v158, 0xbfb8aa3b, v105
	v_exp_f32_e32 v158, v158
	v_rcp_f32_e32 v159, v159
	v_mul_f32_e32 v161, v112, v155
	v_or_b32_e32 v154, 16, v150
	v_add_f32_e32 v155, 1.0, v158
	v_rcp_f32_e32 v155, v155
	v_mul_f32_e32 v158, v109, v159
	v_cndmask_b32_e64 v158, v159, v158, s[42:43]
	v_mul_f32_e32 v0, v98, v0
	v_mul_f32_e32 v156, v99, v156
	v_mul_f32_e32 v162, v101, v158
	v_mul_f32_e32 v158, v105, v155
	v_mul_f32_e32 v151, v110, v151
	v_cndmask_b32_e64 v155, v155, v158, s[42:43]
	v_mad_i64_i32 v[158:159], s[44:45], v154, s50, v[152:153]
	v_cvt_pk_bf16_f32 v154, v0, v156
	v_mul_f32_e32 v0, 0xbfb8aa3b, v90
	v_cvt_pk_bf16_f32 v156, v151, v160
	v_exp_f32_e32 v0, v0
	v_mul_f32_e32 v151, 0xbfb8aa3b, v86
	v_exp_f32_e32 v151, v151
	v_mul_f32_e32 v157, v100, v157
	v_add_f32_e32 v0, 1.0, v0
	v_rcp_f32_e32 v0, v0
	v_add_f32_e32 v151, 1.0, v151
	v_rcp_f32_e32 v151, v151
	v_mul_f32_e32 v163, v113, v155
	v_cvt_pk_bf16_f32 v155, v157, v162
	v_cvt_pk_bf16_f32 v157, v161, v163
	global_store_dwordx4 v[158:159], v[154:157], off nt
	v_mul_f32_e32 v158, 0xbfb8aa3b, v92
	v_exp_f32_e32 v158, v158
	v_mul_f32_e32 v155, v90, v0
	v_cndmask_b32_e64 v0, v0, v155, s[42:43]
	v_mul_f32_e32 v155, v86, v151
	v_mul_f32_e32 v156, 0xbfb8aa3b, v91
	v_exp_f32_e32 v156, v156
	v_cndmask_b32_e64 v151, v151, v155, s[42:43]
	v_mul_f32_e32 v155, 0xbfb8aa3b, v87
	v_exp_f32_e32 v155, v155
	v_add_f32_e32 v156, 1.0, v156
	v_rcp_f32_e32 v156, v156
	v_add_f32_e32 v158, 1.0, v158
	v_add_f32_e32 v155, 1.0, v155
	v_rcp_f32_e32 v155, v155
	v_mul_f32_e32 v157, v91, v156
	v_cndmask_b32_e64 v156, v156, v157, s[42:43]
	v_rcp_f32_e32 v158, v158
	v_mul_f32_e32 v157, v87, v155
	v_cndmask_b32_e64 v155, v155, v157, s[42:43]
	v_mul_f32_e32 v157, 0xbfb8aa3b, v88
	v_exp_f32_e32 v157, v157
	v_mul_f32_e32 v160, v95, v155
	v_mul_f32_e32 v159, 0xbfb8aa3b, v93
	v_exp_f32_e32 v159, v159
	v_add_f32_e32 v155, 1.0, v157
	v_rcp_f32_e32 v155, v155
	v_mul_f32_e32 v157, v92, v158
	v_cndmask_b32_e64 v157, v158, v157, s[42:43]
	v_add_f32_e32 v159, 1.0, v159
	v_mul_f32_e32 v158, v88, v155
	v_cndmask_b32_e64 v155, v155, v158, s[42:43]
	v_mul_f32_e32 v158, 0xbfb8aa3b, v89
	v_exp_f32_e32 v158, v158
	v_rcp_f32_e32 v159, v159
; __device__ __forceinline__ float sigmoidf_(float x) { return __builtin_amdgcn_rcpf(1.0f + __expf(-x)); }
;     __device__ __forceinline__ void operator()(f32x4 (&acc)[2][2][4][2], const Unit& u, int wr, int wc, int fr, int fq) const {
;     ...
;         if (act >= 3) {
;             const int row0 = u.pm * BM + wr * 64 + fr, col0 = colt + wc * 32 + 8 * fq;
; #pragma unroll
;             for (int ai = 0; ai < 2; ++ai)
; #pragma unroll
;                 for (int m = 0; m < 4; ++m) { bf16_t* rowp = base + (size_t)(row0 + ai * HALF + m * 16) * ldc + col0;
;                     f32x4 v0 = acc[ai][0][m][0], v1 = acc[ai][0][m][1]; const f32x4 g0 = acc[ai][1][m][0], g1 = acc[ai][1][m][1];
; #pragma unroll
;                     for (int j = 0; j < 4; ++j) { const float s0 = sigmoidf_(g0[j]), s1 = sigmoidf_(g1[j]);
;                         v0[j] *= (act == 3) ? g0[j] * s0 : s0; v1[j] *= (act == 3) ? g1[j] * s1 : s1; }
;                     u32x4 w; w.x = pk2(v0[0], v0[1]); w.y = pk2(v0[2], v0[3]); w.z = pk2(v1[0], v1[1]); w.w = pk2(v1[2], v1[3]);
;                     *(u32x4*)rowp = w; }
;             return;
	v_mul_f32_e32 v161, v96, v155
	v_or_b32_e32 v154, 32, v150
	v_add_f32_e32 v155, 1.0, v158
	v_rcp_f32_e32 v155, v155
	v_mul_f32_e32 v158, v93, v159
	v_cndmask_b32_e64 v158, v159, v158, s[42:43]
	v_mul_f32_e32 v0, v82, v0
	v_mul_f32_e32 v156, v83, v156
	v_mul_f32_e32 v162, v85, v158
	v_mul_f32_e32 v158, v89, v155
	v_mul_f32_e32 v151, v94, v151
	v_cndmask_b32_e64 v155, v155, v158, s[42:43]
	v_mad_i64_i32 v[158:159], s[44:45], v154, s50, v[152:153]
	v_cvt_pk_bf16_f32 v154, v0, v156
	v_mul_f32_e32 v0, 0xbfb8aa3b, v74
	v_cvt_pk_bf16_f32 v156, v151, v160
	v_exp_f32_e32 v0, v0
	v_mul_f32_e32 v151, 0xbfb8aa3b, v70
	v_exp_f32_e32 v151, v151
	v_mul_f32_e32 v157, v84, v157
	v_add_f32_e32 v0, 1.0, v0
	v_rcp_f32_e32 v0, v0
	v_add_f32_e32 v151, 1.0, v151
	v_rcp_f32_e32 v151, v151
	v_mul_f32_e32 v163, v97, v155
	v_cvt_pk_bf16_f32 v155, v157, v162
	v_cvt_pk_bf16_f32 v157, v161, v163
	global_store_dwordx4 v[158:159], v[154:157], off nt
	v_mul_f32_e32 v158, 0xbfb8aa3b, v76
	v_exp_f32_e32 v158, v158
	v_mul_f32_e32 v155, v74, v0
	v_cndmask_b32_e64 v0, v0, v155, s[42:43]
	v_mul_f32_e32 v155, v70, v151
	v_mul_f32_e32 v156, 0xbfb8aa3b, v75
	v_exp_f32_e32 v156, v156
	v_cndmask_b32_e64 v151, v151, v155, s[42:43]
	v_mul_f32_e32 v155, 0xbfb8aa3b, v71
	v_exp_f32_e32 v155, v155
	v_add_f32_e32 v156, 1.0, v156
	v_rcp_f32_e32 v156, v156
	v_add_f32_e32 v158, 1.0, v158
	v_add_f32_e32 v155, 1.0, v155
	v_rcp_f32_e32 v155, v155
	v_mul_f32_e32 v157, v75, v156
	v_cndmask_b32_e64 v156, v156, v157, s[42:43]
	v_rcp_f32_e32 v158, v158
	v_mul_f32_e32 v157, v71, v155
	v_cndmask_b32_e64 v155, v155, v157, s[42:43]
	v_mul_f32_e32 v157, 0xbfb8aa3b, v72
	v_exp_f32_e32 v157, v157
	v_mul_f32_e32 v160, v79, v155
	v_mul_f32_e32 v159, 0xbfb8aa3b, v77
	v_exp_f32_e32 v159, v159
	v_add_f32_e32 v155, 1.0, v157
	v_rcp_f32_e32 v155, v155
	v_mul_f32_e32 v157, v76, v158
	v_cndmask_b32_e64 v157, v158, v157, s[42:43]
	v_add_f32_e32 v159, 1.0, v159
	v_mul_f32_e32 v158, v72, v155
	v_cndmask_b32_e64 v155, v155, v158, s[42:43]
	v_mul_f32_e32 v158, 0xbfb8aa3b, v73
	v_exp_f32_e32 v158, v158
	v_rcp_f32_e32 v159, v159
	v_mul_f32_e32 v161, v80, v155
	v_or_b32_e32 v154, 48, v150
	v_add_f32_e32 v155, 1.0, v158
	v_rcp_f32_e32 v155, v155
	v_mul_f32_e32 v158, v77, v159
	v_cndmask_b32_e64 v158, v159, v158, s[42:43]
	v_mul_f32_e32 v0, v66, v0
	v_mul_f32_e32 v156, v67, v156
	v_mul_f32_e32 v162, v69, v158
	v_mul_f32_e32 v158, v73, v155
	v_mul_f32_e32 v151, v78, v151
	v_cndmask_b32_e64 v155, v155, v158, s[42:43]
	v_mad_i64_i32 v[158:159], s[44:45], v154, s50, v[152:153]
	v_cvt_pk_bf16_f32 v154, v0, v156
	v_mul_f32_e32 v0, 0xbfb8aa3b, v58
	v_cvt_pk_bf16_f32 v156, v151, v160
	v_exp_f32_e32 v0, v0
	v_mul_f32_e32 v151, 0xbfb8aa3b, v54
	v_exp_f32_e32 v151, v151
	v_mul_f32_e32 v157, v68, v157
	v_add_f32_e32 v0, 1.0, v0
	v_rcp_f32_e32 v0, v0
	v_add_f32_e32 v151, 1.0, v151
	v_rcp_f32_e32 v151, v151
	v_mul_f32_e32 v163, v81, v155
	v_cvt_pk_bf16_f32 v155, v157, v162
	v_cvt_pk_bf16_f32 v157, v161, v163
	global_store_dwordx4 v[158:159], v[154:157], off nt
	v_mul_f32_e32 v158, 0xbfb8aa3b, v60
	v_exp_f32_e32 v158, v158
	v_mul_f32_e32 v155, v58, v0
	v_cndmask_b32_e64 v0, v0, v155, s[42:43]
	v_mul_f32_e32 v155, v54, v151
	v_mul_f32_e32 v156, 0xbfb8aa3b, v59
	v_exp_f32_e32 v156, v156
	v_cndmask_b32_e64 v151, v151, v155, s[42:43]
	v_mul_f32_e32 v155, 0xbfb8aa3b, v55
	v_exp_f32_e32 v155, v155
	v_add_f32_e32 v156, 1.0, v156
	v_rcp_f32_e32 v156, v156
	v_add_f32_e32 v158, 1.0, v158
	v_add_f32_e32 v155, 1.0, v155
	v_rcp_f32_e32 v155, v155
	v_mul_f32_e32 v157, v59, v156
	v_cndmask_b32_e64 v156, v156, v157, s[42:43]
	v_rcp_f32_e32 v158, v158
	v_mul_f32_e32 v157, v55, v155
	v_cndmask_b32_e64 v155, v155, v157, s[42:43]
	v_mul_f32_e32 v157, 0xbfb8aa3b, v56
	v_exp_f32_e32 v157, v157
	v_mul_f32_e32 v160, v63, v155
	v_mul_f32_e32 v159, 0xbfb8aa3b, v61
	v_exp_f32_e32 v159, v159
	v_add_f32_e32 v155, 1.0, v157
	v_rcp_f32_e32 v155, v155
	v_mul_f32_e32 v157, v60, v158
	v_cndmask_b32_e64 v157, v158, v157, s[42:43]
	v_add_f32_e32 v159, 1.0, v159
	v_mul_f32_e32 v158, v56, v155
	v_cndmask_b32_e64 v155, v155, v158, s[42:43]
	v_mul_f32_e32 v158, 0xbfb8aa3b, v57
	v_exp_f32_e32 v158, v158
	v_rcp_f32_e32 v159, v159
	v_mul_f32_e32 v161, v64, v155
	v_add_u32_e32 v154, 0x80, v150
	v_add_f32_e32 v155, 1.0, v158
	v_rcp_f32_e32 v155, v155
	v_mul_f32_e32 v158, v61, v159
	v_cndmask_b32_e64 v158, v159, v158, s[42:43]
	v_mul_f32_e32 v0, v50, v0
	v_mul_f32_e32 v156, v51, v156
	v_mul_f32_e32 v162, v53, v158
	v_mul_f32_e32 v158, v57, v155
	v_mul_f32_e32 v151, v62, v151
	v_cndmask_b32_e64 v155, v155, v158, s[42:43]
	v_mad_i64_i32 v[158:159], s[44:45], v154, s50, v[152:153]
	v_cvt_pk_bf16_f32 v154, v0, v156
	v_mul_f32_e32 v0, 0xbfb8aa3b, v42
	v_cvt_pk_bf16_f32 v156, v151, v160
	v_exp_f32_e32 v0, v0
	v_mul_f32_e32 v151, 0xbfb8aa3b, v38
	v_exp_f32_e32 v151, v151
	v_mul_f32_e32 v157, v52, v157
	v_add_f32_e32 v0, 1.0, v0
	v_rcp_f32_e32 v0, v0
	v_add_f32_e32 v151, 1.0, v151
	v_rcp_f32_e32 v151, v151
	v_mul_f32_e32 v163, v65, v155
	v_cvt_pk_bf16_f32 v155, v157, v162
	v_cvt_pk_bf16_f32 v157, v161, v163
	global_store_dwordx4 v[158:159], v[154:157], off nt
	v_mul_f32_e32 v158, 0xbfb8aa3b, v44
	v_exp_f32_e32 v158, v158
	v_mul_f32_e32 v155, v42, v0
	v_cndmask_b32_e64 v0, v0, v155, s[42:43]
	v_mul_f32_e32 v155, v38, v151
	v_mul_f32_e32 v156, 0xbfb8aa3b, v43
	v_exp_f32_e32 v156, v156
	v_cndmask_b32_e64 v151, v151, v155, s[42:43]
	v_mul_f32_e32 v155, 0xbfb8aa3b, v39
	v_exp_f32_e32 v155, v155
	v_add_f32_e32 v156, 1.0, v156
	v_rcp_f32_e32 v156, v156
	v_add_f32_e32 v158, 1.0, v158
	v_add_f32_e32 v155, 1.0, v155
; __device__ __forceinline__ float sigmoidf_(float x) { return __builtin_amdgcn_rcpf(1.0f + __expf(-x)); }
;     __device__ __forceinline__ void operator()(f32x4 (&acc)[2][2][4][2], const Unit& u, int wr, int wc, int fr, int fq) const {
;     ...
;         if (act >= 3) {
;             const int row0 = u.pm * BM + wr * 64 + fr, col0 = colt + wc * 32 + 8 * fq;
; #pragma unroll
;             for (int ai = 0; ai < 2; ++ai)
; #pragma unroll
;                 for (int m = 0; m < 4; ++m) { bf16_t* rowp = base + (size_t)(row0 + ai * HALF + m * 16) * ldc + col0;
;                     f32x4 v0 = acc[ai][0][m][0], v1 = acc[ai][0][m][1]; const f32x4 g0 = acc[ai][1][m][0], g1 = acc[ai][1][m][1];
; #pragma unroll
;                     for (int j = 0; j < 4; ++j) { const float s0 = sigmoidf_(g0[j]), s1 = sigmoidf_(g1[j]);
;                         v0[j] *= (act == 3) ? g0[j] * s0 : s0; v1[j] *= (act == 3) ? g1[j] * s1 : s1; }
;                     u32x4 w; w.x = pk2(v0[0], v0[1]); w.y = pk2(v0[2], v0[3]); w.z = pk2(v1[0], v1[1]); w.w = pk2(v1[2], v1[3]);
;                     *(u32x4*)rowp = w; }
;             return;
	v_rcp_f32_e32 v155, v155
	v_mul_f32_e32 v157, v43, v156
	v_cndmask_b32_e64 v156, v156, v157, s[42:43]
	v_rcp_f32_e32 v158, v158
	v_mul_f32_e32 v157, v39, v155
	v_cndmask_b32_e64 v155, v155, v157, s[42:43]
	v_mul_f32_e32 v157, 0xbfb8aa3b, v40
	v_exp_f32_e32 v157, v157
	v_mul_f32_e32 v160, v47, v155
	v_mul_f32_e32 v159, 0xbfb8aa3b, v45
	v_exp_f32_e32 v159, v159
	v_add_f32_e32 v155, 1.0, v157
	v_rcp_f32_e32 v155, v155
	v_mul_f32_e32 v157, v44, v158
	v_cndmask_b32_e64 v157, v158, v157, s[42:43]
	v_add_f32_e32 v159, 1.0, v159
	v_mul_f32_e32 v158, v40, v155
	v_cndmask_b32_e64 v155, v155, v158, s[42:43]
	v_mul_f32_e32 v158, 0xbfb8aa3b, v41
	v_exp_f32_e32 v158, v158
	v_rcp_f32_e32 v159, v159
	v_mul_f32_e32 v161, v48, v155
	v_add_u32_e32 v154, 0x90, v150
	v_add_f32_e32 v155, 1.0, v158
	v_rcp_f32_e32 v155, v155
	v_mul_f32_e32 v158, v45, v159
	v_cndmask_b32_e64 v158, v159, v158, s[42:43]
	v_mul_f32_e32 v0, v34, v0
	v_mul_f32_e32 v156, v35, v156
	v_mul_f32_e32 v162, v37, v158
	v_mul_f32_e32 v158, v41, v155
	v_mul_f32_e32 v151, v46, v151
	v_cndmask_b32_e64 v155, v155, v158, s[42:43]
	v_mad_i64_i32 v[158:159], s[44:45], v154, s50, v[152:153]
	v_cvt_pk_bf16_f32 v154, v0, v156
	v_mul_f32_e32 v0, 0xbfb8aa3b, v26
	v_cvt_pk_bf16_f32 v156, v151, v160
	v_exp_f32_e32 v0, v0
	v_mul_f32_e32 v151, 0xbfb8aa3b, v22
	v_exp_f32_e32 v151, v151
	v_mul_f32_e32 v157, v36, v157
	v_add_f32_e32 v0, 1.0, v0
	v_rcp_f32_e32 v0, v0
	v_add_f32_e32 v151, 1.0, v151
	v_rcp_f32_e32 v151, v151
	v_mul_f32_e32 v163, v49, v155
	v_cvt_pk_bf16_f32 v155, v157, v162
	v_cvt_pk_bf16_f32 v157, v161, v163
	global_store_dwordx4 v[158:159], v[154:157], off nt
	v_mul_f32_e32 v158, 0xbfb8aa3b, v28
	v_exp_f32_e32 v158, v158
	v_mul_f32_e32 v155, v26, v0
	v_cndmask_b32_e64 v0, v0, v155, s[42:43]
	v_mul_f32_e32 v155, v22, v151
	v_mul_f32_e32 v156, 0xbfb8aa3b, v27
	v_exp_f32_e32 v156, v156
	v_cndmask_b32_e64 v151, v151, v155, s[42:43]
	v_mul_f32_e32 v155, 0xbfb8aa3b, v23
	v_exp_f32_e32 v155, v155
	v_add_f32_e32 v156, 1.0, v156
	v_rcp_f32_e32 v156, v156
	v_add_f32_e32 v158, 1.0, v158
	v_add_f32_e32 v155, 1.0, v155
	v_rcp_f32_e32 v155, v155
	v_mul_f32_e32 v157, v27, v156
	v_cndmask_b32_e64 v156, v156, v157, s[42:43]
	v_rcp_f32_e32 v158, v158
	v_mul_f32_e32 v157, v23, v155
	v_cndmask_b32_e64 v155, v155, v157, s[42:43]
	v_mul_f32_e32 v157, 0xbfb8aa3b, v24
	v_exp_f32_e32 v157, v157
	v_mul_f32_e32 v160, v31, v155
	v_mul_f32_e32 v159, 0xbfb8aa3b, v29
	v_exp_f32_e32 v159, v159
	v_add_f32_e32 v155, 1.0, v157
	v_rcp_f32_e32 v155, v155
	v_mul_f32_e32 v157, v28, v158
	v_cndmask_b32_e64 v157, v158, v157, s[42:43]
	v_add_f32_e32 v159, 1.0, v159
	v_mul_f32_e32 v158, v24, v155
	v_cndmask_b32_e64 v155, v155, v158, s[42:43]
	v_mul_f32_e32 v158, 0xbfb8aa3b, v25
	v_exp_f32_e32 v158, v158
	v_rcp_f32_e32 v159, v159
	v_mul_f32_e32 v161, v32, v155
	v_add_u32_e32 v154, 0xa0, v150
	v_add_f32_e32 v155, 1.0, v158
	v_rcp_f32_e32 v155, v155
	v_mul_f32_e32 v158, v29, v159
	v_cndmask_b32_e64 v158, v159, v158, s[42:43]
	v_mul_f32_e32 v0, v18, v0
	v_mul_f32_e32 v156, v19, v156
	v_mul_f32_e32 v162, v21, v158
	v_mul_f32_e32 v158, v25, v155
	v_mul_f32_e32 v151, v30, v151
	v_cndmask_b32_e64 v155, v155, v158, s[42:43]
	v_mad_i64_i32 v[158:159], s[44:45], v154, s50, v[152:153]
	v_cvt_pk_bf16_f32 v154, v0, v156
	v_mul_f32_e32 v0, 0xbfb8aa3b, v10
	v_cvt_pk_bf16_f32 v156, v151, v160
	v_exp_f32_e32 v0, v0
	v_mul_f32_e32 v151, 0xbfb8aa3b, v6
	v_exp_f32_e32 v151, v151
	v_mul_f32_e32 v157, v20, v157
	v_add_f32_e32 v0, 1.0, v0
	v_rcp_f32_e32 v0, v0
	v_add_f32_e32 v151, 1.0, v151
	v_rcp_f32_e32 v151, v151
	v_mul_f32_e32 v163, v33, v155
	v_cvt_pk_bf16_f32 v155, v157, v162
	v_cvt_pk_bf16_f32 v157, v161, v163
	global_store_dwordx4 v[158:159], v[154:157], off nt
	v_mul_f32_e32 v160, 0xbfb8aa3b, v13
	v_exp_f32_e32 v160, v160
	v_mul_f32_e32 v155, v10, v0
	v_mul_f32_e32 v156, 0xbfb8aa3b, v11
	v_cndmask_b32_e64 v0, v0, v155, s[42:43]
	v_mul_f32_e32 v155, v6, v151
	v_exp_f32_e32 v156, v156
	v_cndmask_b32_e64 v151, v151, v155, s[42:43]
	v_mul_f32_e32 v155, 0xbfb8aa3b, v7
	v_exp_f32_e32 v155, v155
	v_add_f32_e32 v156, 1.0, v156
	v_rcp_f32_e32 v156, v156
	v_add_f32_e32 v160, 1.0, v160
	v_add_f32_e32 v155, 1.0, v155
	v_rcp_f32_e32 v155, v155
	v_mul_f32_e32 v157, v11, v156
	v_cndmask_b32_e64 v156, v156, v157, s[42:43]
	v_mul_f32_e32 v157, 0xbfb8aa3b, v12
	v_mul_f32_e32 v158, v3, v156
	v_mul_f32_e32 v156, v7, v155
	v_exp_f32_e32 v157, v157
	v_cndmask_b32_e64 v155, v155, v156, s[42:43]
	v_mul_f32_e32 v156, 0xbfb8aa3b, v8
	v_exp_f32_e32 v156, v156
	v_add_f32_e32 v157, 1.0, v157
	v_rcp_f32_e32 v157, v157
	v_rcp_f32_e32 v160, v160
	v_add_f32_e32 v156, 1.0, v156
	v_rcp_f32_e32 v156, v156
	v_mul_f32_e32 v159, v12, v157
	v_cndmask_b32_e64 v157, v157, v159, s[42:43]
	v_mul_f32_e32 v159, v4, v157
	v_mul_f32_e32 v157, v8, v156
	v_cndmask_b32_e64 v156, v156, v157, s[42:43]
	v_mul_f32_e32 v157, 0xbfb8aa3b, v9
	v_exp_f32_e32 v157, v157
	v_mul_f32_e32 v161, v16, v156
	v_add_u32_e32 v154, 0xb0, v150
	v_mul_f32_e32 v0, v2, v0
	v_add_f32_e32 v156, 1.0, v157
	v_rcp_f32_e32 v156, v156
	v_mul_f32_e32 v157, v13, v160
	v_cndmask_b32_e64 v157, v160, v157, s[42:43]
	v_mul_f32_e32 v160, v5, v157
	v_mul_f32_e32 v157, v9, v156
	v_cndmask_b32_e64 v156, v156, v157, s[42:43]
	v_mul_f32_e32 v151, v14, v151
	v_mul_f32_e32 v155, v15, v155
	v_mul_f32_e32 v162, v17, v156
	v_mad_i64_i32 v[156:157], s[42:43], v154, s50, v[152:153]
	v_cvt_pk_bf16_f32 v152, v0, v158
	v_cvt_pk_bf16_f32 v153, v159, v160
	v_cvt_pk_bf16_f32 v154, v151, v155
	v_cvt_pk_bf16_f32 v155, v161, v162
	global_store_dwordx4 v[156:157], v[152:155], off nt

;     __device__ __forceinline__ void operator()(f32x4 (&acc)[2][2][4][2], const Unit& u, int wr, int wc, int fr, int fq) const {
;     ...
;         if (pn >= 41) {
;             const int row0 = u.pm * BM + wr * 64 + fr, d0 = (pn - 41) * 64 + wc * 16 + 4 * fq;
; #pragma unroll
;             for (int ai = 0; ai < 2; ++ai)
; #pragma unroll
;                 for (int m = 0; m < 4; ++m) { bf16_t* rowp = HG + (size_t)(row0 + ai * HALF + m * 16) * HGW + d0;
;                     u32x2 w[4];
; #pragma unroll
;                     for (int jp = 0; jp < 2; ++jp) { float r[2][4];
; #pragma unroll
;                         for (int jj = 0; jj < 2; ++jj) { const int j = 2 * jp + jj; float e[4];
; #pragma unroll
;                             for (int i = 0; i < 4; ++i) e[i] = 1.0f + __expf(-fminf(fmaxf(acc[ai][i >> 1][m][i & 1][j], -30.f), 30.f));
;                             r[jj][0] = e[1] * __builtin_amdgcn_rcpf(e[0]); r[jj][1] = e[2] * __builtin_amdgcn_rcpf(e[1]); r[jj][2] = e[3] * __builtin_amdgcn_rcpf(e[2]); r[jj][3] = __builtin_amdgcn_rcpf(e[3]); }
; #pragma unroll
;                         for (int k = 0; k < 4; ++k) { const unsigned pk = pk2(r[0][k], r[1][k]); if (jp == 0) w[k].x = pk; else w[k].y = pk; } }
; #pragma unroll
;                     for (int k = 0; k < 4; ++k) *(u32x2*)(rowp + k * 2048) = w[k];
;                     asm volatile("" ::: "memory"); }
;             return;
.LBB0_300:
	v_max_f32_e32 v114, v114, v114
	v_max_f32_e32 v115, v115, v115
	v_med3_f32 v114, v114, s73, v170
	v_med3_f32 v115, v115, s73, v170
	v_mul_f32_e32 v114, 0xbfb8aa3b, v114
	v_mul_f32_e32 v115, 0xbfb8aa3b, v115
	v_exp_f32_e32 v114, v114
	v_exp_f32_e32 v115, v115
	v_max_f32_e32 v126, v126, v126
	v_max_f32_e32 v127, v127, v127
	v_med3_f32 v126, v126, s73, v170
	v_med3_f32 v127, v127, s73, v170
	v_mul_f32_e32 v126, 0xbfb8aa3b, v126
	v_max_f32_e32 v122, v122, v122
	v_mul_f32_e32 v127, 0xbfb8aa3b, v127
	v_max_f32_e32 v123, v123, v123
	v_exp_f32_e32 v126, v126
	v_med3_f32 v122, v122, s73, v170
	v_exp_f32_e32 v127, v127
	v_med3_f32 v123, v123, s73, v170
	v_add_f32_e32 v114, 1.0, v114
	v_add_f32_e32 v115, 1.0, v115
	v_mul_f32_e32 v122, 0xbfb8aa3b, v122
	v_mul_f32_e32 v123, 0xbfb8aa3b, v123
	v_rcp_f32_e32 v114, v114
	v_rcp_f32_e32 v115, v115
	v_exp_f32_e32 v122, v122
	v_exp_f32_e32 v123, v123
	v_max_f32_e32 v118, v118, v118
	v_max_f32_e32 v119, v119, v119
	v_med3_f32 v118, v118, s73, v170
	v_med3_f32 v119, v119, s73, v170
	v_pk_add_f32 v[126:127], v[126:127], 1.0 op_sel_hi:[1,0]
	v_mul_f32_e32 v118, 0xbfb8aa3b, v118
	v_mul_f32_e32 v119, 0xbfb8aa3b, v119
	v_pk_mul_f32 v[114:115], v[126:127], v[114:115]
	v_exp_f32_e32 v118, v118
	v_exp_f32_e32 v119, v119
	v_rcp_f32_e32 v154, v126
	v_rcp_f32_e32 v155, v127
	v_cvt_pk_bf16_f32 v126, v114, v115
	v_pk_add_f32 v[114:115], v[122:123], 1.0 op_sel_hi:[1,0]
	v_max_f32_e32 v116, v116, v116
	v_rcp_f32_e32 v122, v114
	v_rcp_f32_e32 v123, v115
	v_pk_mul_f32 v[154:155], v[114:115], v[154:155]
	v_pk_add_f32 v[114:115], v[118:119], 1.0 op_sel_hi:[1,0]
	v_max_f32_e32 v117, v117, v117
	v_rcp_f32_e32 v119, v114
	v_rcp_f32_e32 v127, v115
	v_pk_mul_f32 v[114:115], v[114:115], v[122:123]
	v_med3_f32 v116, v116, s73, v170
	v_cvt_pk_bf16_f32 v122, v114, v115
	v_max_f32_e32 v115, v124, v124
	v_med3_f32 v115, v115, s73, v170
	v_mul_f32_e32 v115, 0xbfb8aa3b, v115
	v_exp_f32_e32 v124, v115
	v_max_f32_e32 v115, v120, v120
	v_med3_f32 v117, v117, s73, v170
	v_med3_f32 v115, v115, s73, v170
	v_mul_f32_e32 v116, 0xbfb8aa3b, v116
	v_mul_f32_e32 v117, 0xbfb8aa3b, v117
	v_mul_f32_e32 v115, 0xbfb8aa3b, v115
	v_exp_f32_e32 v116, v116
	v_exp_f32_e32 v117, v117
	v_max_f32_e32 v114, v128, v128
	v_exp_f32_e32 v120, v115
	v_max_f32_e32 v115, v129, v129
	v_med3_f32 v114, v114, s73, v170
	v_med3_f32 v115, v115, s73, v170
	v_cvt_pk_bf16_f32 v118, v154, v155
	v_cvt_pk_bf16_f32 v154, v119, v127
	v_mul_f32_e32 v114, 0xbfb8aa3b, v114
	v_mul_f32_e32 v115, 0xbfb8aa3b, v115
	v_max_f32_e32 v119, v125, v125
	v_exp_f32_e32 v114, v114
	v_exp_f32_e32 v115, v115
	v_med3_f32 v119, v119, s73, v170
	v_add_f32_e32 v116, 1.0, v116
	v_add_f32_e32 v117, 1.0, v117
	v_mul_f32_e32 v119, 0xbfb8aa3b, v119
	v_rcp_f32_e32 v116, v116
	v_rcp_f32_e32 v117, v117
	v_exp_f32_e32 v125, v119
	v_max_f32_e32 v119, v121, v121
	v_med3_f32 v119, v119, s73, v170
	v_pk_add_f32 v[114:115], v[114:115], 1.0 op_sel_hi:[1,0]
	v_mul_f32_e32 v119, 0xbfb8aa3b, v119
	v_rcp_f32_e32 v128, v114
	v_rcp_f32_e32 v129, v115
	v_pk_mul_f32 v[114:115], v[114:115], v[116:117]
	v_exp_f32_e32 v121, v119
	v_cvt_pk_bf16_f32 v127, v114, v115
	v_pk_add_f32 v[114:115], v[124:125], 1.0 op_sel_hi:[1,0]
	v_lshl_add_u32 v0, s69, 6, v175
	v_rcp_f32_e32 v116, v114
	v_rcp_f32_e32 v117, v115
	v_pk_mul_f32 v[124:125], v[114:115], v[128:129]
	v_pk_add_f32 v[114:115], v[120:121], 1.0 op_sel_hi:[1,0]
	v_max_f32_e32 v98, v98, v98
	v_rcp_f32_e32 v120, v114
	v_rcp_f32_e32 v121, v115
	v_pk_mul_f32 v[114:115], v[114:115], v[116:117]
	v_lshlrev_b64 v[116:117], 1, v[0:1]
	v_max_f32_e32 v0, v110, v110
	v_med3_f32 v0, v0, s73, v170
	v_mul_f32_e32 v0, 0xbfb8aa3b, v0
	v_exp_f32_e32 v110, v0
	v_max_f32_e32 v0, v106, v106
	v_med3_f32 v0, v0, s73, v170
	v_mul_f32_e32 v0, 0xbfb8aa3b, v0
	v_exp_f32_e32 v106, v0
	v_max_f32_e32 v0, v102, v102
	v_med3_f32 v0, v0, s73, v170
	v_mul_f32_e32 v0, 0xbfb8aa3b, v0
	v_exp_f32_e32 v102, v0
	v_max_f32_e32 v0, v111, v111
	v_med3_f32 v0, v0, s73, v170
	v_mul_f32_e32 v0, 0xbfb8aa3b, v0
	v_exp_f32_e32 v111, v0
	v_max_f32_e32 v0, v107, v107
	v_med3_f32 v98, v98, s73, v170
	v_max_f32_e32 v99, v99, v99
	v_med3_f32 v0, v0, s73, v170
	v_mul_f32_e32 v98, 0xbfb8aa3b, v98
	v_med3_f32 v99, v99, s73, v170
	v_mul_f32_e32 v0, 0xbfb8aa3b, v0
	v_exp_f32_e32 v98, v98
	v_mul_f32_e32 v99, 0xbfb8aa3b, v99
	v_exp_f32_e32 v107, v0
	v_max_f32_e32 v0, v103, v103
	v_exp_f32_e32 v99, v99
	v_med3_f32 v0, v0, s73, v170
	v_mul_f32_e32 v0, 0xbfb8aa3b, v0
	v_exp_f32_e32 v103, v0
	v_add_f32_e32 v0, 1.0, v98
	v_ashrrev_i32_e32 v151, 31, v150
	v_rcp_f32_e32 v98, v0
	v_add_f32_e32 v0, 1.0, v99
	v_lshlrev_b64 v[152:153], 14, v[150:151]
	v_rcp_f32_e32 v99, v0
	v_lshl_add_u64 v[152:153], s[36:37], 0, v[152:153]
	v_cvt_pk_bf16_f32 v123, v114, v115
	v_lshl_add_u64 v[114:115], v[152:153], 0, v[116:117]
	v_cvt_pk_bf16_f32 v155, v120, v121
	v_add_co_u32_e32 v120, vcc, s33, v114
	v_pk_add_f32 v[110:111], v[110:111], 1.0 op_sel_hi:[1,0]
	v_cvt_pk_bf16_f32 v119, v124, v125
	v_addc_co_u32_e32 v121, vcc, 0, v115, vcc
	v_pk_mul_f32 v[98:99], v[110:111], v[98:99]
	v_pk_add_f32 v[106:107], v[106:107], 1.0 op_sel_hi:[1,0]
	v_pk_add_f32 v[102:103], v[102:103], 1.0 op_sel_hi:[1,0]
	global_store_dwordx2 v[114:115], v[126:127], off nt
	global_store_dwordx2 v[120:121], v[118:119], off offset:-4096 nt
	global_store_dwordx2 v[120:121], v[122:123], off nt
	v_rcp_f32_e32 v120, v110
	v_rcp_f32_e32 v121, v111
	v_cvt_pk_bf16_f32 v98, v98, v99
	v_rcp_f32_e32 v110, v106
	v_rcp_f32_e32 v111, v107
	v_rcp_f32_e32 v0, v102
	v_rcp_f32_e32 v99, v103
	v_pk_mul_f32 v[120:121], v[106:107], v[120:121]
	v_pk_mul_f32 v[102:103], v[102:103], v[110:111]
;     __device__ __forceinline__ void operator()(f32x4 (&acc)[2][2][4][2], const Unit& u, int wr, int wc, int fr, int fq) const {
;     ...
;         if (pn >= 41) {
;             const int row0 = u.pm * BM + wr * 64 + fr, d0 = (pn - 41) * 64 + wc * 16 + 4 * fq;
; #pragma unroll
;             for (int ai = 0; ai < 2; ++ai)
; #pragma unroll
;                 for (int m = 0; m < 4; ++m) { bf16_t* rowp = HG + (size_t)(row0 + ai * HALF + m * 16) * HGW + d0;
;                     u32x2 w[4];
; #pragma unroll
;                     for (int jp = 0; jp < 2; ++jp) { float r[2][4];
; #pragma unroll
;                         for (int jj = 0; jj < 2; ++jj) { const int j = 2 * jp + jj; float e[4];
; #pragma unroll
;                             for (int i = 0; i < 4; ++i) e[i] = 1.0f + __expf(-fminf(fmaxf(acc[ai][i >> 1][m][i & 1][j], -30.f), 30.f));
;                             r[jj][0] = e[1] * __builtin_amdgcn_rcpf(e[0]); r[jj][1] = e[2] * __builtin_amdgcn_rcpf(e[1]); r[jj][2] = e[3] * __builtin_amdgcn_rcpf(e[2]); r[jj][3] = __builtin_amdgcn_rcpf(e[3]); }
; #pragma unroll
;                         for (int k = 0; k < 4; ++k) { const unsigned pk = pk2(r[0][k], r[1][k]); if (jp == 0) w[k].x = pk; else w[k].y = pk; } }
; #pragma unroll
;                     for (int k = 0; k < 4; ++k) *(u32x2*)(rowp + k * 2048) = w[k];
;                     asm volatile("" ::: "memory"); }
;             return;
	v_cvt_pk_bf16_f32 v106, v120, v121
	v_cvt_pk_bf16_f32 v110, v0, v99
	v_max_f32_e32 v0, v112, v112
	v_med3_f32 v0, v0, s73, v170
	v_mul_f32_e32 v0, 0xbfb8aa3b, v0
	v_exp_f32_e32 v112, v0
	v_max_f32_e32 v0, v108, v108
	v_med3_f32 v0, v0, s73, v170
	v_mul_f32_e32 v0, 0xbfb8aa3b, v0
	v_exp_f32_e32 v108, v0
	v_max_f32_e32 v0, v104, v104
	v_med3_f32 v0, v0, s73, v170
	v_mul_f32_e32 v0, 0xbfb8aa3b, v0
	v_exp_f32_e32 v104, v0
	v_max_f32_e32 v0, v113, v113
	v_med3_f32 v0, v0, s73, v170
	v_mul_f32_e32 v0, 0xbfb8aa3b, v0
	v_max_f32_e32 v99, v100, v100
	v_exp_f32_e32 v113, v0
	v_max_f32_e32 v0, v109, v109
	v_med3_f32 v99, v99, s73, v170
	v_max_f32_e32 v100, v101, v101
	v_med3_f32 v0, v0, s73, v170
	v_mul_f32_e32 v99, 0xbfb8aa3b, v99
	v_med3_f32 v100, v100, s73, v170
	v_mul_f32_e32 v0, 0xbfb8aa3b, v0
	v_exp_f32_e32 v99, v99
	v_mul_f32_e32 v100, 0xbfb8aa3b, v100
	v_exp_f32_e32 v109, v0
	v_max_f32_e32 v0, v105, v105
	v_exp_f32_e32 v101, v100
	v_med3_f32 v0, v0, s73, v170
	v_mul_f32_e32 v0, 0xbfb8aa3b, v0
	v_exp_f32_e32 v105, v0
	v_add_f32_e32 v0, 1.0, v99
	v_rcp_f32_e32 v100, v0
	v_add_f32_e32 v0, 1.0, v101
	v_rcp_f32_e32 v101, v0
	v_pk_add_f32 v[112:113], v[112:113], 1.0 op_sel_hi:[1,0]
	v_max_f32_e32 v82, v82, v82
	v_rcp_f32_e32 v120, v112
	v_rcp_f32_e32 v121, v113
	v_pk_mul_f32 v[100:101], v[112:113], v[100:101]
	v_med3_f32 v82, v82, s73, v170
	v_cvt_pk_bf16_f32 v99, v100, v101
	v_pk_add_f32 v[100:101], v[108:109], 1.0 op_sel_hi:[1,0]
	v_max_f32_e32 v83, v83, v83
	v_rcp_f32_e32 v108, v100
	v_pk_mul_f32 v[112:113], v[100:101], v[120:121]
	v_rcp_f32_e32 v109, v101
	v_pk_add_f32 v[100:101], v[104:105], 1.0 op_sel_hi:[1,0]
	v_mul_f32_e32 v82, 0xbfb8aa3b, v82
	v_rcp_f32_e32 v0, v100
	v_rcp_f32_e32 v104, v101
	v_med3_f32 v83, v83, s73, v170
	v_exp_f32_e32 v82, v82
	v_mul_f32_e32 v83, 0xbfb8aa3b, v83
	v_cvt_pk_bf16_f32 v111, v0, v104
	v_max_f32_e32 v0, v94, v94
	v_med3_f32 v0, v0, s73, v170
	v_mul_f32_e32 v0, 0xbfb8aa3b, v0
	v_exp_f32_e32 v94, v0
	v_max_f32_e32 v0, v90, v90
	v_med3_f32 v0, v0, s73, v170
	v_mul_f32_e32 v0, 0xbfb8aa3b, v0
	v_exp_f32_e32 v90, v0
	v_max_f32_e32 v0, v86, v86
	v_med3_f32 v0, v0, s73, v170
	v_mul_f32_e32 v0, 0xbfb8aa3b, v0
	v_exp_f32_e32 v86, v0
	v_max_f32_e32 v0, v95, v95
	v_med3_f32 v0, v0, s73, v170
	v_mul_f32_e32 v0, 0xbfb8aa3b, v0
	v_exp_f32_e32 v95, v0
	v_max_f32_e32 v0, v91, v91
	v_med3_f32 v0, v0, s73, v170
	v_mul_f32_e32 v0, 0xbfb8aa3b, v0
	v_add_co_u32_e32 v118, vcc, s52, v114
	v_exp_f32_e32 v91, v0
	v_max_f32_e32 v0, v87, v87
	v_exp_f32_e32 v83, v83
	v_addc_co_u32_e32 v119, vcc, 0, v115, vcc
	v_med3_f32 v0, v0, s73, v170
	global_store_dwordx2 v[118:119], v[154:155], off nt
	v_or_b32_e32 v118, 16, v150
	v_mul_f32_e32 v0, 0xbfb8aa3b, v0
	v_ashrrev_i32_e32 v119, 31, v118
	v_exp_f32_e32 v87, v0
	v_add_f32_e32 v0, 1.0, v82
	v_lshlrev_b64 v[118:119], 14, v[118:119]
	v_rcp_f32_e32 v82, v0
	v_add_f32_e32 v0, 1.0, v83
	v_lshl_add_u64 v[118:119], s[36:37], 0, v[118:119]
	v_pk_mul_f32 v[100:101], v[100:101], v[108:109]
	v_rcp_f32_e32 v83, v0
	v_cvt_pk_bf16_f32 v102, v102, v103
	v_cvt_pk_bf16_f32 v103, v100, v101
	v_lshl_add_u64 v[100:101], v[118:119], 0, v[116:117]
	global_store_dwordx2 v[100:101], v[98:99], off nt
	v_add_co_u32_e32 v98, vcc, s33, v100
	v_cvt_pk_bf16_f32 v107, v112, v113
	s_nop 0
	v_addc_co_u32_e32 v99, vcc, 0, v101, vcc
	v_pk_add_f32 v[94:95], v[94:95], 1.0 op_sel_hi:[1,0]
	global_store_dwordx2 v[98:99], v[106:107], off offset:-4096 nt
	global_store_dwordx2 v[98:99], v[102:103], off nt
	v_add_co_u32_e32 v98, vcc, s52, v100
	v_pk_mul_f32 v[82:83], v[94:95], v[82:83]
	v_pk_add_f32 v[90:91], v[90:91], 1.0 op_sel_hi:[1,0]
	v_pk_add_f32 v[86:87], v[86:87], 1.0 op_sel_hi:[1,0]
	v_addc_co_u32_e32 v99, vcc, 0, v101, vcc
	v_rcp_f32_e32 v100, v94
	v_rcp_f32_e32 v101, v95
	v_cvt_pk_bf16_f32 v82, v82, v83
	v_rcp_f32_e32 v94, v90
	v_rcp_f32_e32 v95, v91
	v_rcp_f32_e32 v0, v86
	v_rcp_f32_e32 v83, v87
	v_pk_mul_f32 v[100:101], v[90:91], v[100:101]
	v_pk_mul_f32 v[86:87], v[86:87], v[94:95]
	v_cvt_pk_bf16_f32 v90, v100, v101
	v_cvt_pk_bf16_f32 v94, v0, v83
	v_max_f32_e32 v0, v96, v96
	v_med3_f32 v0, v0, s73, v170
	v_mul_f32_e32 v0, 0xbfb8aa3b, v0
	v_exp_f32_e32 v96, v0
	v_max_f32_e32 v0, v92, v92
	v_med3_f32 v0, v0, s73, v170
	v_mul_f32_e32 v0, 0xbfb8aa3b, v0
	v_exp_f32_e32 v92, v0
	v_max_f32_e32 v0, v88, v88
	v_med3_f32 v0, v0, s73, v170
	v_mul_f32_e32 v0, 0xbfb8aa3b, v0
	v_exp_f32_e32 v88, v0
	v_max_f32_e32 v0, v97, v97
	v_med3_f32 v0, v0, s73, v170
	v_mul_f32_e32 v0, 0xbfb8aa3b, v0
	v_max_f32_e32 v83, v84, v84
	v_exp_f32_e32 v97, v0
	v_max_f32_e32 v0, v93, v93
	v_med3_f32 v83, v83, s73, v170
	v_max_f32_e32 v84, v85, v85
	v_med3_f32 v0, v0, s73, v170
	v_mul_f32_e32 v83, 0xbfb8aa3b, v83
	v_med3_f32 v84, v84, s73, v170
	v_mul_f32_e32 v0, 0xbfb8aa3b, v0
	v_exp_f32_e32 v83, v83
	v_mul_f32_e32 v84, 0xbfb8aa3b, v84
	v_exp_f32_e32 v93, v0
	v_max_f32_e32 v0, v89, v89
	v_exp_f32_e32 v85, v84
	v_med3_f32 v0, v0, s73, v170
	v_mul_f32_e32 v0, 0xbfb8aa3b, v0
	v_exp_f32_e32 v89, v0
	v_add_f32_e32 v0, 1.0, v83
	v_rcp_f32_e32 v84, v0
	v_add_f32_e32 v0, 1.0, v85
	v_rcp_f32_e32 v85, v0
	v_pk_add_f32 v[96:97], v[96:97], 1.0 op_sel_hi:[1,0]
	v_max_f32_e32 v66, v66, v66
	v_rcp_f32_e32 v100, v96
	v_rcp_f32_e32 v101, v97
	v_pk_mul_f32 v[84:85], v[96:97], v[84:85]
	v_med3_f32 v66, v66, s73, v170
	v_cvt_pk_bf16_f32 v83, v84, v85
	v_pk_add_f32 v[84:85], v[92:93], 1.0 op_sel_hi:[1,0]
	v_max_f32_e32 v67, v67, v67
	v_rcp_f32_e32 v92, v84
	v_pk_mul_f32 v[96:97], v[84:85], v[100:101]
	v_rcp_f32_e32 v93, v85
	v_pk_add_f32 v[84:85], v[88:89], 1.0 op_sel_hi:[1,0]
	v_mul_f32_e32 v66, 0xbfb8aa3b, v66
	v_rcp_f32_e32 v0, v84
	v_rcp_f32_e32 v88, v85
;     __device__ __forceinline__ void operator()(f32x4 (&acc)[2][2][4][2], const Unit& u, int wr, int wc, int fr, int fq) const {
;     ...
;         if (pn >= 41) {
;             const int row0 = u.pm * BM + wr * 64 + fr, d0 = (pn - 41) * 64 + wc * 16 + 4 * fq;
; #pragma unroll
;             for (int ai = 0; ai < 2; ++ai)
; #pragma unroll
;                 for (int m = 0; m < 4; ++m) { bf16_t* rowp = HG + (size_t)(row0 + ai * HALF + m * 16) * HGW + d0;
;                     u32x2 w[4];
; #pragma unroll
;                     for (int jp = 0; jp < 2; ++jp) { float r[2][4];
; #pragma unroll
;                         for (int jj = 0; jj < 2; ++jj) { const int j = 2 * jp + jj; float e[4];
; #pragma unroll
;                             for (int i = 0; i < 4; ++i) e[i] = 1.0f + __expf(-fminf(fmaxf(acc[ai][i >> 1][m][i & 1][j], -30.f), 30.f));
;                             r[jj][0] = e[1] * __builtin_amdgcn_rcpf(e[0]); r[jj][1] = e[2] * __builtin_amdgcn_rcpf(e[1]); r[jj][2] = e[3] * __builtin_amdgcn_rcpf(e[2]); r[jj][3] = __builtin_amdgcn_rcpf(e[3]); }
; #pragma unroll
;                         for (int k = 0; k < 4; ++k) { const unsigned pk = pk2(r[0][k], r[1][k]); if (jp == 0) w[k].x = pk; else w[k].y = pk; } }
; #pragma unroll
;                     for (int k = 0; k < 4; ++k) *(u32x2*)(rowp + k * 2048) = w[k];
;                     asm volatile("" ::: "memory"); }
;             return;
	v_med3_f32 v67, v67, s73, v170
	v_exp_f32_e32 v66, v66
	v_mul_f32_e32 v67, 0xbfb8aa3b, v67
	v_cvt_pk_bf16_f32 v95, v0, v88
	v_max_f32_e32 v0, v78, v78
	v_med3_f32 v0, v0, s73, v170
	v_mul_f32_e32 v0, 0xbfb8aa3b, v0
	v_exp_f32_e32 v78, v0
	v_max_f32_e32 v0, v74, v74
	v_med3_f32 v0, v0, s73, v170
	v_mul_f32_e32 v0, 0xbfb8aa3b, v0
	v_exp_f32_e32 v74, v0
	v_max_f32_e32 v0, v70, v70
	v_med3_f32 v0, v0, s73, v170
	v_mul_f32_e32 v0, 0xbfb8aa3b, v0
	v_exp_f32_e32 v70, v0
	v_max_f32_e32 v0, v79, v79
	v_med3_f32 v0, v0, s73, v170
	v_mul_f32_e32 v0, 0xbfb8aa3b, v0
	v_exp_f32_e32 v79, v0
	v_max_f32_e32 v0, v75, v75
	v_med3_f32 v0, v0, s73, v170
	v_mul_f32_e32 v0, 0xbfb8aa3b, v0
	v_exp_f32_e32 v75, v0
	v_max_f32_e32 v0, v71, v71
	v_exp_f32_e32 v67, v67
	v_med3_f32 v0, v0, s73, v170
	global_store_dwordx2 v[98:99], v[110:111], off nt
	v_or_b32_e32 v98, 32, v150
	v_mul_f32_e32 v0, 0xbfb8aa3b, v0
	v_ashrrev_i32_e32 v99, 31, v98
	v_exp_f32_e32 v71, v0
	v_add_f32_e32 v0, 1.0, v66
	v_lshlrev_b64 v[98:99], 14, v[98:99]
	v_rcp_f32_e32 v66, v0
	v_add_f32_e32 v0, 1.0, v67
	v_lshl_add_u64 v[98:99], s[36:37], 0, v[98:99]
	v_pk_mul_f32 v[84:85], v[84:85], v[92:93]
	v_rcp_f32_e32 v67, v0
	v_cvt_pk_bf16_f32 v86, v86, v87
	v_cvt_pk_bf16_f32 v87, v84, v85
	v_lshl_add_u64 v[84:85], v[98:99], 0, v[116:117]
	global_store_dwordx2 v[84:85], v[82:83], off nt
	v_add_co_u32_e32 v82, vcc, s33, v84
	v_cvt_pk_bf16_f32 v91, v96, v97
	s_nop 0
	v_addc_co_u32_e32 v83, vcc, 0, v85, vcc
	v_pk_add_f32 v[78:79], v[78:79], 1.0 op_sel_hi:[1,0]
	global_store_dwordx2 v[82:83], v[90:91], off offset:-4096 nt
	global_store_dwordx2 v[82:83], v[86:87], off nt
	v_add_co_u32_e32 v82, vcc, s52, v84
	v_pk_mul_f32 v[66:67], v[78:79], v[66:67]
	v_pk_add_f32 v[74:75], v[74:75], 1.0 op_sel_hi:[1,0]
	v_pk_add_f32 v[70:71], v[70:71], 1.0 op_sel_hi:[1,0]
	v_addc_co_u32_e32 v83, vcc, 0, v85, vcc
	v_rcp_f32_e32 v84, v78
	v_rcp_f32_e32 v85, v79
	v_cvt_pk_bf16_f32 v66, v66, v67
	v_rcp_f32_e32 v78, v74
	v_rcp_f32_e32 v79, v75
	v_rcp_f32_e32 v0, v70
	v_rcp_f32_e32 v67, v71
	v_pk_mul_f32 v[84:85], v[74:75], v[84:85]
	v_pk_mul_f32 v[70:71], v[70:71], v[78:79]
	v_cvt_pk_bf16_f32 v74, v84, v85
	v_cvt_pk_bf16_f32 v78, v0, v67
	v_max_f32_e32 v0, v80, v80
	v_med3_f32 v0, v0, s73, v170
	v_mul_f32_e32 v0, 0xbfb8aa3b, v0
	v_exp_f32_e32 v80, v0
	v_max_f32_e32 v0, v76, v76
	v_med3_f32 v0, v0, s73, v170
	v_mul_f32_e32 v0, 0xbfb8aa3b, v0
	v_exp_f32_e32 v76, v0
	v_max_f32_e32 v0, v72, v72
	v_med3_f32 v0, v0, s73, v170
	v_mul_f32_e32 v0, 0xbfb8aa3b, v0
	v_exp_f32_e32 v72, v0
	v_max_f32_e32 v0, v81, v81
	v_med3_f32 v0, v0, s73, v170
	v_mul_f32_e32 v0, 0xbfb8aa3b, v0
	v_max_f32_e32 v67, v68, v68
	v_exp_f32_e32 v81, v0
	v_max_f32_e32 v0, v77, v77
	v_med3_f32 v67, v67, s73, v170
	v_max_f32_e32 v68, v69, v69
	v_med3_f32 v0, v0, s73, v170
	v_mul_f32_e32 v67, 0xbfb8aa3b, v67
	v_med3_f32 v68, v68, s73, v170
	v_mul_f32_e32 v0, 0xbfb8aa3b, v0
	v_exp_f32_e32 v67, v67
	v_mul_f32_e32 v68, 0xbfb8aa3b, v68
	v_exp_f32_e32 v77, v0
	v_max_f32_e32 v0, v73, v73
	v_exp_f32_e32 v69, v68
	v_med3_f32 v0, v0, s73, v170
	v_mul_f32_e32 v0, 0xbfb8aa3b, v0
	v_exp_f32_e32 v73, v0
	v_add_f32_e32 v0, 1.0, v67
	v_rcp_f32_e32 v68, v0
	v_add_f32_e32 v0, 1.0, v69
	v_rcp_f32_e32 v69, v0
	v_pk_add_f32 v[80:81], v[80:81], 1.0 op_sel_hi:[1,0]
	v_max_f32_e32 v50, v50, v50
	v_rcp_f32_e32 v84, v80
	v_rcp_f32_e32 v85, v81
	v_pk_mul_f32 v[68:69], v[80:81], v[68:69]
	v_med3_f32 v50, v50, s73, v170
	v_cvt_pk_bf16_f32 v67, v68, v69
	v_pk_add_f32 v[68:69], v[76:77], 1.0 op_sel_hi:[1,0]
	v_max_f32_e32 v51, v51, v51
	v_rcp_f32_e32 v76, v68
	v_pk_mul_f32 v[80:81], v[68:69], v[84:85]
	v_rcp_f32_e32 v77, v69
	v_pk_add_f32 v[68:69], v[72:73], 1.0 op_sel_hi:[1,0]
	v_mul_f32_e32 v50, 0xbfb8aa3b, v50
	v_rcp_f32_e32 v0, v68
	v_rcp_f32_e32 v72, v69
	v_med3_f32 v51, v51, s73, v170
	v_exp_f32_e32 v50, v50
	v_mul_f32_e32 v51, 0xbfb8aa3b, v51
	v_cvt_pk_bf16_f32 v79, v0, v72
	v_max_f32_e32 v0, v62, v62
	v_med3_f32 v0, v0, s73, v170
	v_mul_f32_e32 v0, 0xbfb8aa3b, v0
	v_exp_f32_e32 v62, v0
	v_max_f32_e32 v0, v58, v58
	v_med3_f32 v0, v0, s73, v170
	v_mul_f32_e32 v0, 0xbfb8aa3b, v0
	v_exp_f32_e32 v58, v0
	v_max_f32_e32 v0, v54, v54
	v_med3_f32 v0, v0, s73, v170
	v_mul_f32_e32 v0, 0xbfb8aa3b, v0
	v_exp_f32_e32 v54, v0
	v_max_f32_e32 v0, v63, v63
	v_med3_f32 v0, v0, s73, v170
	v_mul_f32_e32 v0, 0xbfb8aa3b, v0
	v_exp_f32_e32 v63, v0
	v_max_f32_e32 v0, v59, v59
	v_med3_f32 v0, v0, s73, v170
	v_mul_f32_e32 v0, 0xbfb8aa3b, v0
	v_exp_f32_e32 v59, v0
	v_max_f32_e32 v0, v55, v55
	v_exp_f32_e32 v51, v51
	global_store_dwordx2 v[82:83], v[94:95], off nt
	v_or_b32_e32 v82, 48, v150
	v_med3_f32 v0, v0, s73, v170
	v_ashrrev_i32_e32 v83, 31, v82
	v_mul_f32_e32 v0, 0xbfb8aa3b, v0
	v_lshlrev_b64 v[82:83], 14, v[82:83]
	v_exp_f32_e32 v55, v0
	v_add_f32_e32 v0, 1.0, v50
	v_lshl_add_u64 v[82:83], s[36:37], 0, v[82:83]
	v_pk_mul_f32 v[68:69], v[68:69], v[76:77]
	v_rcp_f32_e32 v50, v0
	v_add_f32_e32 v0, 1.0, v51
	v_cvt_pk_bf16_f32 v70, v70, v71
	v_cvt_pk_bf16_f32 v71, v68, v69
	v_lshl_add_u64 v[68:69], v[82:83], 0, v[116:117]
	v_rcp_f32_e32 v51, v0
	global_store_dwordx2 v[68:69], v[66:67], off nt
	v_add_co_u32_e32 v66, vcc, s33, v68
	v_cvt_pk_bf16_f32 v75, v80, v81
	s_nop 0
	v_addc_co_u32_e32 v67, vcc, 0, v69, vcc
	global_store_dwordx2 v[66:67], v[74:75], off offset:-4096 nt
	global_store_dwordx2 v[66:67], v[70:71], off nt
	v_add_co_u32_e32 v66, vcc, s52, v68
	v_pk_add_f32 v[62:63], v[62:63], 1.0 op_sel_hi:[1,0]
	s_nop 0
	v_addc_co_u32_e32 v67, vcc, 0, v69, vcc
	v_pk_mul_f32 v[50:51], v[62:63], v[50:51]
	v_pk_add_f32 v[58:59], v[58:59], 1.0 op_sel_hi:[1,0]
	v_pk_add_f32 v[54:55], v[54:55], 1.0 op_sel_hi:[1,0]
;     __device__ __forceinline__ void operator()(f32x4 (&acc)[2][2][4][2], const Unit& u, int wr, int wc, int fr, int fq) const {
;     ...
;         if (pn >= 41) {
;             const int row0 = u.pm * BM + wr * 64 + fr, d0 = (pn - 41) * 64 + wc * 16 + 4 * fq;
; #pragma unroll
;             for (int ai = 0; ai < 2; ++ai)
; #pragma unroll
;                 for (int m = 0; m < 4; ++m) { bf16_t* rowp = HG + (size_t)(row0 + ai * HALF + m * 16) * HGW + d0;
;                     u32x2 w[4];
; #pragma unroll
;                     for (int jp = 0; jp < 2; ++jp) { float r[2][4];
; #pragma unroll
;                         for (int jj = 0; jj < 2; ++jj) { const int j = 2 * jp + jj; float e[4];
; #pragma unroll
;                             for (int i = 0; i < 4; ++i) e[i] = 1.0f + __expf(-fminf(fmaxf(acc[ai][i >> 1][m][i & 1][j], -30.f), 30.f));
;                             r[jj][0] = e[1] * __builtin_amdgcn_rcpf(e[0]); r[jj][1] = e[2] * __builtin_amdgcn_rcpf(e[1]); r[jj][2] = e[3] * __builtin_amdgcn_rcpf(e[2]); r[jj][3] = __builtin_amdgcn_rcpf(e[3]); }
; #pragma unroll
;                         for (int k = 0; k < 4; ++k) { const unsigned pk = pk2(r[0][k], r[1][k]); if (jp == 0) w[k].x = pk; else w[k].y = pk; } }
; #pragma unroll
;                     for (int k = 0; k < 4; ++k) *(u32x2*)(rowp + k * 2048) = w[k];
;                     asm volatile("" ::: "memory"); }
;             return;
	global_store_dwordx2 v[66:67], v[78:79], off nt
	v_rcp_f32_e32 v66, v62
	v_rcp_f32_e32 v67, v63
	v_cvt_pk_bf16_f32 v50, v50, v51
	v_rcp_f32_e32 v62, v58
	v_rcp_f32_e32 v63, v59
	v_rcp_f32_e32 v0, v54
	v_rcp_f32_e32 v51, v55
	v_pk_mul_f32 v[66:67], v[58:59], v[66:67]
	v_pk_mul_f32 v[54:55], v[54:55], v[62:63]
	v_cvt_pk_bf16_f32 v58, v66, v67
	v_cvt_pk_bf16_f32 v62, v0, v51
	v_max_f32_e32 v0, v64, v64
	v_med3_f32 v0, v0, s73, v170
	v_mul_f32_e32 v0, 0xbfb8aa3b, v0
	v_exp_f32_e32 v64, v0
	v_max_f32_e32 v0, v60, v60
	v_med3_f32 v0, v0, s73, v170
	v_mul_f32_e32 v0, 0xbfb8aa3b, v0
	v_exp_f32_e32 v60, v0
	v_max_f32_e32 v0, v56, v56
	v_med3_f32 v0, v0, s73, v170
	v_mul_f32_e32 v0, 0xbfb8aa3b, v0
	v_exp_f32_e32 v56, v0
	v_max_f32_e32 v0, v65, v65
	v_med3_f32 v0, v0, s73, v170
	v_mul_f32_e32 v0, 0xbfb8aa3b, v0
	v_max_f32_e32 v51, v52, v52
	v_exp_f32_e32 v65, v0
	v_max_f32_e32 v0, v61, v61
	v_med3_f32 v51, v51, s73, v170
	v_max_f32_e32 v52, v53, v53
	v_med3_f32 v0, v0, s73, v170
	v_mul_f32_e32 v51, 0xbfb8aa3b, v51
	v_med3_f32 v52, v52, s73, v170
	v_mul_f32_e32 v0, 0xbfb8aa3b, v0
	v_exp_f32_e32 v51, v51
	v_mul_f32_e32 v52, 0xbfb8aa3b, v52
	v_exp_f32_e32 v61, v0
	v_max_f32_e32 v0, v57, v57
	v_exp_f32_e32 v53, v52
	v_med3_f32 v0, v0, s73, v170
	v_mul_f32_e32 v0, 0xbfb8aa3b, v0
	v_exp_f32_e32 v57, v0
	v_add_f32_e32 v0, 1.0, v51
	v_rcp_f32_e32 v52, v0
	v_add_f32_e32 v0, 1.0, v53
	v_rcp_f32_e32 v53, v0
	v_pk_add_f32 v[64:65], v[64:65], 1.0 op_sel_hi:[1,0]
	v_max_f32_e32 v34, v34, v34
	v_rcp_f32_e32 v66, v64
	v_rcp_f32_e32 v67, v65
	v_pk_mul_f32 v[52:53], v[64:65], v[52:53]
	v_med3_f32 v34, v34, s73, v170
	v_cvt_pk_bf16_f32 v51, v52, v53
	v_pk_add_f32 v[52:53], v[60:61], 1.0 op_sel_hi:[1,0]
	v_max_f32_e32 v35, v35, v35
	v_rcp_f32_e32 v60, v52
	v_pk_mul_f32 v[64:65], v[52:53], v[66:67]
	v_rcp_f32_e32 v61, v53
	v_pk_add_f32 v[52:53], v[56:57], 1.0 op_sel_hi:[1,0]
	v_mul_f32_e32 v34, 0xbfb8aa3b, v34
	v_rcp_f32_e32 v0, v52
	v_rcp_f32_e32 v56, v53
	v_med3_f32 v35, v35, s73, v170
	v_exp_f32_e32 v34, v34
	v_mul_f32_e32 v35, 0xbfb8aa3b, v35
	v_cvt_pk_bf16_f32 v63, v0, v56
	v_max_f32_e32 v0, v46, v46
	v_med3_f32 v0, v0, s73, v170
	v_mul_f32_e32 v0, 0xbfb8aa3b, v0
	v_exp_f32_e32 v46, v0
	v_max_f32_e32 v0, v42, v42
	v_med3_f32 v0, v0, s73, v170
	v_mul_f32_e32 v0, 0xbfb8aa3b, v0
	v_exp_f32_e32 v42, v0
	v_max_f32_e32 v0, v38, v38
	v_med3_f32 v0, v0, s73, v170
	v_mul_f32_e32 v0, 0xbfb8aa3b, v0
	v_exp_f32_e32 v38, v0
	v_max_f32_e32 v0, v47, v47
	v_med3_f32 v0, v0, s73, v170
	v_mul_f32_e32 v0, 0xbfb8aa3b, v0
	v_exp_f32_e32 v47, v0
	v_max_f32_e32 v0, v43, v43
	v_med3_f32 v0, v0, s73, v170
	v_mul_f32_e32 v0, 0xbfb8aa3b, v0
	v_exp_f32_e32 v43, v0
	v_max_f32_e32 v0, v39, v39
	v_exp_f32_e32 v35, v35
	v_med3_f32 v0, v0, s73, v170
	v_mul_f32_e32 v0, 0xbfb8aa3b, v0
	v_exp_f32_e32 v39, v0
	v_add_f32_e32 v0, 1.0, v34
	v_rcp_f32_e32 v34, v0
	v_add_f32_e32 v0, 1.0, v35
	v_pk_mul_f32 v[52:53], v[52:53], v[60:61]
	s_mov_b32 s24, 0x201000
	v_rcp_f32_e32 v35, v0
	v_cvt_pk_bf16_f32 v54, v54, v55
	v_cvt_pk_bf16_f32 v55, v52, v53
	v_add_co_u32_e32 v52, vcc, s24, v114
	s_mov_b32 s24, 0x203000
	s_nop 0
	v_addc_co_u32_e32 v53, vcc, 0, v115, vcc
	v_cvt_pk_bf16_f32 v59, v64, v65
	global_store_dwordx2 v[52:53], v[50:51], off offset:-4096 nt
	global_store_dwordx2 v[52:53], v[58:59], off nt
	v_add_co_u32_e32 v50, vcc, s24, v114
	v_pk_add_f32 v[46:47], v[46:47], 1.0 op_sel_hi:[1,0]
	s_nop 0
	v_addc_co_u32_e32 v51, vcc, 0, v115, vcc
	v_pk_mul_f32 v[34:35], v[46:47], v[34:35]
	v_pk_add_f32 v[42:43], v[42:43], 1.0 op_sel_hi:[1,0]
	v_pk_add_f32 v[38:39], v[38:39], 1.0 op_sel_hi:[1,0]
	global_store_dwordx2 v[50:51], v[54:55], off offset:-4096 nt
	global_store_dwordx2 v[50:51], v[62:63], off nt
	v_rcp_f32_e32 v50, v46
	v_rcp_f32_e32 v51, v47
	v_cvt_pk_bf16_f32 v34, v34, v35
	v_rcp_f32_e32 v46, v42
	v_rcp_f32_e32 v47, v43
	v_rcp_f32_e32 v0, v38
	v_rcp_f32_e32 v35, v39
	v_pk_mul_f32 v[50:51], v[42:43], v[50:51]
	v_pk_mul_f32 v[38:39], v[38:39], v[46:47]
	v_cvt_pk_bf16_f32 v42, v50, v51
	v_cvt_pk_bf16_f32 v46, v0, v35
	v_max_f32_e32 v0, v48, v48
	v_med3_f32 v0, v0, s73, v170
	v_mul_f32_e32 v0, 0xbfb8aa3b, v0
	v_exp_f32_e32 v48, v0
	v_max_f32_e32 v0, v44, v44
	v_med3_f32 v0, v0, s73, v170
	v_mul_f32_e32 v0, 0xbfb8aa3b, v0
	v_exp_f32_e32 v44, v0
	v_max_f32_e32 v0, v40, v40
	v_med3_f32 v0, v0, s73, v170
	v_mul_f32_e32 v0, 0xbfb8aa3b, v0
	v_exp_f32_e32 v40, v0
	v_max_f32_e32 v0, v49, v49
	v_med3_f32 v0, v0, s73, v170
	v_mul_f32_e32 v0, 0xbfb8aa3b, v0
	v_max_f32_e32 v35, v36, v36
	v_exp_f32_e32 v49, v0
	v_max_f32_e32 v0, v45, v45
	v_med3_f32 v35, v35, s73, v170
	v_max_f32_e32 v36, v37, v37
	v_med3_f32 v0, v0, s73, v170
	v_mul_f32_e32 v35, 0xbfb8aa3b, v35
	v_med3_f32 v36, v36, s73, v170
	v_mul_f32_e32 v0, 0xbfb8aa3b, v0
	v_exp_f32_e32 v35, v35
	v_mul_f32_e32 v36, 0xbfb8aa3b, v36
	v_exp_f32_e32 v45, v0
	v_max_f32_e32 v0, v41, v41
	v_exp_f32_e32 v37, v36
	v_med3_f32 v0, v0, s73, v170
	v_mul_f32_e32 v0, 0xbfb8aa3b, v0
	v_exp_f32_e32 v41, v0
	v_add_f32_e32 v0, 1.0, v35
	v_rcp_f32_e32 v36, v0
	v_add_f32_e32 v0, 1.0, v37
	v_rcp_f32_e32 v37, v0
	v_pk_add_f32 v[48:49], v[48:49], 1.0 op_sel_hi:[1,0]
	v_max_f32_e32 v18, v18, v18
	v_rcp_f32_e32 v50, v48
	v_rcp_f32_e32 v51, v49
	v_pk_mul_f32 v[36:37], v[48:49], v[36:37]
	v_med3_f32 v18, v18, s73, v170
	v_cvt_pk_bf16_f32 v35, v36, v37
	v_pk_add_f32 v[36:37], v[44:45], 1.0 op_sel_hi:[1,0]
	v_max_f32_e32 v19, v19, v19
	v_rcp_f32_e32 v44, v36
	v_pk_mul_f32 v[48:49], v[36:37], v[50:51]
	v_rcp_f32_e32 v45, v37
	v_pk_add_f32 v[36:37], v[40:41], 1.0 op_sel_hi:[1,0]
	v_mul_f32_e32 v18, 0xbfb8aa3b, v18
	v_rcp_f32_e32 v0, v36
	v_rcp_f32_e32 v40, v37
	v_med3_f32 v19, v19, s73, v170
;     __device__ __forceinline__ void operator()(f32x4 (&acc)[2][2][4][2], const Unit& u, int wr, int wc, int fr, int fq) const {
;     ...
;         if (pn >= 41) {
;             const int row0 = u.pm * BM + wr * 64 + fr, d0 = (pn - 41) * 64 + wc * 16 + 4 * fq;
; #pragma unroll
;             for (int ai = 0; ai < 2; ++ai)
; #pragma unroll
;                 for (int m = 0; m < 4; ++m) { bf16_t* rowp = HG + (size_t)(row0 + ai * HALF + m * 16) * HGW + d0;
;                     u32x2 w[4];
; #pragma unroll
;                     for (int jp = 0; jp < 2; ++jp) { float r[2][4];
; #pragma unroll
;                         for (int jj = 0; jj < 2; ++jj) { const int j = 2 * jp + jj; float e[4];
; #pragma unroll
;                             for (int i = 0; i < 4; ++i) e[i] = 1.0f + __expf(-fminf(fmaxf(acc[ai][i >> 1][m][i & 1][j], -30.f), 30.f));
;                             r[jj][0] = e[1] * __builtin_amdgcn_rcpf(e[0]); r[jj][1] = e[2] * __builtin_amdgcn_rcpf(e[1]); r[jj][2] = e[3] * __builtin_amdgcn_rcpf(e[2]); r[jj][3] = __builtin_amdgcn_rcpf(e[3]); }
; #pragma unroll
;                         for (int k = 0; k < 4; ++k) { const unsigned pk = pk2(r[0][k], r[1][k]); if (jp == 0) w[k].x = pk; else w[k].y = pk; } }
; #pragma unroll
;                     for (int k = 0; k < 4; ++k) *(u32x2*)(rowp + k * 2048) = w[k];
;                     asm volatile("" ::: "memory"); }
;             return;
	v_exp_f32_e32 v18, v18
	v_mul_f32_e32 v19, 0xbfb8aa3b, v19
	v_cvt_pk_bf16_f32 v47, v0, v40
	v_max_f32_e32 v0, v30, v30
	v_med3_f32 v0, v0, s73, v170
	v_mul_f32_e32 v0, 0xbfb8aa3b, v0
	v_exp_f32_e32 v30, v0
	v_max_f32_e32 v0, v26, v26
	v_med3_f32 v0, v0, s73, v170
	v_mul_f32_e32 v0, 0xbfb8aa3b, v0
	v_exp_f32_e32 v26, v0
	v_max_f32_e32 v0, v22, v22
	v_med3_f32 v0, v0, s73, v170
	v_mul_f32_e32 v0, 0xbfb8aa3b, v0
	v_exp_f32_e32 v22, v0
	v_max_f32_e32 v0, v31, v31
	v_med3_f32 v0, v0, s73, v170
	v_mul_f32_e32 v0, 0xbfb8aa3b, v0
	v_exp_f32_e32 v31, v0
	v_max_f32_e32 v0, v27, v27
	v_med3_f32 v0, v0, s73, v170
	v_mul_f32_e32 v0, 0xbfb8aa3b, v0
	v_exp_f32_e32 v27, v0
	v_max_f32_e32 v0, v23, v23
	v_exp_f32_e32 v19, v19
	v_med3_f32 v0, v0, s73, v170
	v_mul_f32_e32 v0, 0xbfb8aa3b, v0
	v_exp_f32_e32 v23, v0
	v_add_f32_e32 v0, 1.0, v18
	v_rcp_f32_e32 v18, v0
	v_add_f32_e32 v0, 1.0, v19
	v_pk_mul_f32 v[36:37], v[36:37], v[44:45]
	s_mov_b32 s24, 0x241000
	v_rcp_f32_e32 v19, v0
	v_cvt_pk_bf16_f32 v38, v38, v39
	v_cvt_pk_bf16_f32 v39, v36, v37
	v_add_co_u32_e32 v36, vcc, s24, v114
	s_mov_b32 s24, 0x243000
	s_nop 0
	v_addc_co_u32_e32 v37, vcc, 0, v115, vcc
	v_cvt_pk_bf16_f32 v43, v48, v49
	global_store_dwordx2 v[36:37], v[34:35], off offset:-4096 nt
	global_store_dwordx2 v[36:37], v[42:43], off nt
	v_add_co_u32_e32 v34, vcc, s24, v114
	v_pk_add_f32 v[30:31], v[30:31], 1.0 op_sel_hi:[1,0]
	s_nop 0
	v_addc_co_u32_e32 v35, vcc, 0, v115, vcc
	v_pk_mul_f32 v[18:19], v[30:31], v[18:19]
	v_pk_add_f32 v[26:27], v[26:27], 1.0 op_sel_hi:[1,0]
	v_pk_add_f32 v[22:23], v[22:23], 1.0 op_sel_hi:[1,0]
	global_store_dwordx2 v[34:35], v[38:39], off offset:-4096 nt
	global_store_dwordx2 v[34:35], v[46:47], off nt
	v_rcp_f32_e32 v34, v30
	v_rcp_f32_e32 v35, v31
	v_cvt_pk_bf16_f32 v18, v18, v19
	v_rcp_f32_e32 v30, v26
	v_rcp_f32_e32 v31, v27
	v_rcp_f32_e32 v0, v22
	v_rcp_f32_e32 v19, v23
	v_pk_mul_f32 v[34:35], v[26:27], v[34:35]
	v_pk_mul_f32 v[22:23], v[22:23], v[30:31]
	v_cvt_pk_bf16_f32 v26, v34, v35
	v_cvt_pk_bf16_f32 v30, v0, v19
	v_max_f32_e32 v0, v32, v32
	v_med3_f32 v0, v0, s73, v170
	v_mul_f32_e32 v0, 0xbfb8aa3b, v0
	v_exp_f32_e32 v32, v0
	v_max_f32_e32 v0, v28, v28
	v_med3_f32 v0, v0, s73, v170
	v_mul_f32_e32 v0, 0xbfb8aa3b, v0
	v_exp_f32_e32 v28, v0
	v_max_f32_e32 v0, v24, v24
	v_med3_f32 v0, v0, s73, v170
	v_mul_f32_e32 v0, 0xbfb8aa3b, v0
	v_exp_f32_e32 v24, v0
	v_max_f32_e32 v0, v33, v33
	v_med3_f32 v0, v0, s73, v170
	v_mul_f32_e32 v0, 0xbfb8aa3b, v0
	v_max_f32_e32 v19, v20, v20
	v_exp_f32_e32 v33, v0
	v_max_f32_e32 v0, v29, v29
	v_med3_f32 v19, v19, s73, v170
	v_max_f32_e32 v20, v21, v21
	v_med3_f32 v0, v0, s73, v170
	v_mul_f32_e32 v19, 0xbfb8aa3b, v19
	v_med3_f32 v20, v20, s73, v170
	v_mul_f32_e32 v0, 0xbfb8aa3b, v0
	v_exp_f32_e32 v19, v19
	v_mul_f32_e32 v20, 0xbfb8aa3b, v20
	v_exp_f32_e32 v29, v0
	v_max_f32_e32 v0, v25, v25
	v_exp_f32_e32 v21, v20
	v_med3_f32 v0, v0, s73, v170
	v_mul_f32_e32 v0, 0xbfb8aa3b, v0
	v_exp_f32_e32 v25, v0
	v_add_f32_e32 v0, 1.0, v19
	v_rcp_f32_e32 v20, v0
	v_add_f32_e32 v0, 1.0, v21
	v_rcp_f32_e32 v21, v0
	v_pk_add_f32 v[32:33], v[32:33], 1.0 op_sel_hi:[1,0]
	v_max_f32_e32 v2, v2, v2
	v_rcp_f32_e32 v34, v32
	v_rcp_f32_e32 v35, v33
	v_pk_mul_f32 v[20:21], v[32:33], v[20:21]
	v_med3_f32 v2, v2, s73, v170
	v_cvt_pk_bf16_f32 v19, v20, v21
	v_pk_add_f32 v[20:21], v[28:29], 1.0 op_sel_hi:[1,0]
	v_max_f32_e32 v3, v3, v3
	v_rcp_f32_e32 v28, v20
	v_pk_mul_f32 v[32:33], v[20:21], v[34:35]
	v_rcp_f32_e32 v29, v21
	v_pk_add_f32 v[20:21], v[24:25], 1.0 op_sel_hi:[1,0]
	v_mul_f32_e32 v2, 0xbfb8aa3b, v2
	v_rcp_f32_e32 v0, v20
	v_rcp_f32_e32 v24, v21
	v_med3_f32 v3, v3, s73, v170
	v_exp_f32_e32 v2, v2
	v_mul_f32_e32 v3, 0xbfb8aa3b, v3
	v_cvt_pk_bf16_f32 v31, v0, v24
	v_max_f32_e32 v0, v14, v14
	v_med3_f32 v0, v0, s73, v170
	v_mul_f32_e32 v0, 0xbfb8aa3b, v0
	v_exp_f32_e32 v14, v0
	v_max_f32_e32 v0, v10, v10
	v_med3_f32 v0, v0, s73, v170
; #define PG8_BAR __builtin_amdgcn_s_barrier()
;     __device__ __forceinline__ bool zero_after(const Unit& u) const { return (u.pm >> 6) == 3; }
; template <bool ALIGN_EPI, bool SP2, class Epi, class Sched>
; __device__ __forceinline__ void gemm_phase(LAS unsigned char* lds, const Gemm g, const Sched& S, const Epi& E) {
;     ...
;         E(acc, cur, wr, wc, fr, fq);
;         if (!has_next) break;
;         if (E.zero_after(cur))
; #pragma unroll
;         for (int a = 0; a < 2; ++a)
; #pragma unroll
;             for (int b = 0; b < 2; ++b)
; #pragma unroll
;                 for (int m = 0; m < 4; ++m)
; #pragma unroll
;                     for (int n = 0; n < 2; ++n) acc[a][b][m][n] = (f32x4){0.f, 0.f, 0.f, 0.f};
;         cur = nxt; cA = nA; cB = nB; ++ui;
;         if constexpr (ALIGN_EPI) { if (wr == 1) PG8_BAR; }
;     }
;     __device__ __forceinline__ void operator()(f32x4 (&acc)[2][2][4][2], const Unit& u, int wr, int wc, int fr, int fq) const {
;     ...
;         if (pn >= 41) {
;             const int row0 = u.pm * BM + wr * 64 + fr, d0 = (pn - 41) * 64 + wc * 16 + 4 * fq;
; #pragma unroll
;             for (int ai = 0; ai < 2; ++ai)
; #pragma unroll
;                 for (int m = 0; m < 4; ++m) { bf16_t* rowp = HG + (size_t)(row0 + ai * HALF + m * 16) * HGW + d0;
;                     u32x2 w[4];
; #pragma unroll
;                     for (int jp = 0; jp < 2; ++jp) { float r[2][4];
; #pragma unroll
;                         for (int jj = 0; jj < 2; ++jj) { const int j = 2 * jp + jj; float e[4];
; #pragma unroll
;                             for (int i = 0; i < 4; ++i) e[i] = 1.0f + __expf(-fminf(fmaxf(acc[ai][i >> 1][m][i & 1][j], -30.f), 30.f));
;                             r[jj][0] = e[1] * __builtin_amdgcn_rcpf(e[0]); r[jj][1] = e[2] * __builtin_amdgcn_rcpf(e[1]); r[jj][2] = e[3] * __builtin_amdgcn_rcpf(e[2]); r[jj][3] = __builtin_amdgcn_rcpf(e[3]); }
; #pragma unroll
;                         for (int k = 0; k < 4; ++k) { const unsigned pk = pk2(r[0][k], r[1][k]); if (jp == 0) w[k].x = pk; else w[k].y = pk; } }
; #pragma unroll
;                     for (int k = 0; k < 4; ++k) *(u32x2*)(rowp + k * 2048) = w[k];
;                     asm volatile("" ::: "memory"); }
;             return;
	v_mul_f32_e32 v0, 0xbfb8aa3b, v0
	v_exp_f32_e32 v10, v0
	v_max_f32_e32 v0, v6, v6
	v_med3_f32 v0, v0, s73, v170
	v_mul_f32_e32 v0, 0xbfb8aa3b, v0
	v_exp_f32_e32 v6, v0
	v_max_f32_e32 v0, v15, v15
	v_med3_f32 v0, v0, s73, v170
	v_mul_f32_e32 v0, 0xbfb8aa3b, v0
	v_exp_f32_e32 v15, v0
	v_max_f32_e32 v0, v11, v11
	v_med3_f32 v0, v0, s73, v170
	v_mul_f32_e32 v0, 0xbfb8aa3b, v0
	v_exp_f32_e32 v11, v0
	v_max_f32_e32 v0, v7, v7
	v_exp_f32_e32 v3, v3
	v_med3_f32 v0, v0, s73, v170
	v_mul_f32_e32 v0, 0xbfb8aa3b, v0
	v_exp_f32_e32 v7, v0
	v_add_f32_e32 v0, 1.0, v2
	v_rcp_f32_e32 v2, v0
	v_add_f32_e32 v0, 1.0, v3
	v_pk_mul_f32 v[20:21], v[20:21], v[28:29]
	s_mov_b32 s24, 0x281000
	v_rcp_f32_e32 v3, v0
	v_cvt_pk_bf16_f32 v22, v22, v23
	v_cvt_pk_bf16_f32 v23, v20, v21
	v_add_co_u32_e32 v20, vcc, s24, v114
	s_mov_b32 s24, 0x283000
	s_nop 0
	v_addc_co_u32_e32 v21, vcc, 0, v115, vcc
	v_cvt_pk_bf16_f32 v27, v32, v33
	global_store_dwordx2 v[20:21], v[18:19], off offset:-4096 nt
	global_store_dwordx2 v[20:21], v[26:27], off nt
	v_add_co_u32_e32 v18, vcc, s24, v114
	v_pk_add_f32 v[14:15], v[14:15], 1.0 op_sel_hi:[1,0]
	s_nop 0
	v_addc_co_u32_e32 v19, vcc, 0, v115, vcc
	v_pk_mul_f32 v[2:3], v[14:15], v[2:3]
	v_pk_add_f32 v[10:11], v[10:11], 1.0 op_sel_hi:[1,0]
	v_pk_add_f32 v[6:7], v[6:7], 1.0 op_sel_hi:[1,0]
	global_store_dwordx2 v[18:19], v[22:23], off offset:-4096 nt
	global_store_dwordx2 v[18:19], v[30:31], off nt
	v_rcp_f32_e32 v18, v14
	v_rcp_f32_e32 v19, v15
	v_cvt_pk_bf16_f32 v2, v2, v3
	v_rcp_f32_e32 v14, v10
	v_rcp_f32_e32 v15, v11
	v_rcp_f32_e32 v0, v6
	v_rcp_f32_e32 v3, v7
	v_pk_mul_f32 v[18:19], v[10:11], v[18:19]
	v_pk_mul_f32 v[6:7], v[6:7], v[14:15]
	v_cvt_pk_bf16_f32 v10, v18, v19
	v_cvt_pk_bf16_f32 v14, v0, v3
	v_max_f32_e32 v0, v16, v16
	v_med3_f32 v0, v0, s73, v170
	v_mul_f32_e32 v0, 0xbfb8aa3b, v0
	v_exp_f32_e32 v16, v0
	v_max_f32_e32 v0, v12, v12
	v_med3_f32 v0, v0, s73, v170
	v_mul_f32_e32 v0, 0xbfb8aa3b, v0
	v_exp_f32_e32 v12, v0
	v_max_f32_e32 v0, v8, v8
	v_med3_f32 v0, v0, s73, v170
	v_mul_f32_e32 v0, 0xbfb8aa3b, v0
	v_exp_f32_e32 v8, v0
	v_max_f32_e32 v0, v17, v17
	v_med3_f32 v0, v0, s73, v170
	v_mul_f32_e32 v0, 0xbfb8aa3b, v0
	v_max_f32_e32 v3, v4, v4
	v_exp_f32_e32 v17, v0
	v_max_f32_e32 v0, v13, v13
	v_med3_f32 v3, v3, s73, v170
	v_max_f32_e32 v4, v5, v5
	v_med3_f32 v0, v0, s73, v170
	v_mul_f32_e32 v3, 0xbfb8aa3b, v3
	v_med3_f32 v4, v4, s73, v170
	v_mul_f32_e32 v0, 0xbfb8aa3b, v0
	v_exp_f32_e32 v3, v3
	v_mul_f32_e32 v4, 0xbfb8aa3b, v4
	v_exp_f32_e32 v13, v0
	v_max_f32_e32 v0, v9, v9
	v_exp_f32_e32 v5, v4
	v_med3_f32 v0, v0, s73, v170
	v_mul_f32_e32 v0, 0xbfb8aa3b, v0
	v_exp_f32_e32 v9, v0
	v_add_f32_e32 v0, 1.0, v3
	v_rcp_f32_e32 v4, v0
	v_add_f32_e32 v0, 1.0, v5
	v_rcp_f32_e32 v5, v0
	v_pk_add_f32 v[16:17], v[16:17], 1.0 op_sel_hi:[1,0]
	s_mov_b32 s24, 0x2c1000
	v_rcp_f32_e32 v18, v16
	v_pk_mul_f32 v[4:5], v[16:17], v[4:5]
	v_rcp_f32_e32 v19, v17
	v_cvt_pk_bf16_f32 v3, v4, v5
	v_pk_add_f32 v[4:5], v[12:13], 1.0 op_sel_hi:[1,0]
	v_cvt_pk_bf16_f32 v6, v6, v7
	v_rcp_f32_e32 v12, v4
	v_rcp_f32_e32 v13, v5
	v_pk_mul_f32 v[16:17], v[4:5], v[18:19]
	v_pk_add_f32 v[4:5], v[8:9], 1.0 op_sel_hi:[1,0]
	v_cvt_pk_bf16_f32 v11, v16, v17
	v_rcp_f32_e32 v0, v4
	v_rcp_f32_e32 v8, v5
	v_pk_mul_f32 v[4:5], v[4:5], v[12:13]
	v_cvt_pk_bf16_f32 v15, v0, v8
	v_cvt_pk_bf16_f32 v7, v4, v5
	v_add_co_u32_e32 v4, vcc, s24, v114
	s_nop 1
	v_addc_co_u32_e32 v5, vcc, 0, v115, vcc
	global_store_dwordx2 v[4:5], v[2:3], off offset:-4096 nt
	global_store_dwordx2 v[4:5], v[10:11], off nt
	v_add_co_u32_e32 v2, vcc, 0x2c2000, v114
	s_nop 1
	v_addc_co_u32_e32 v3, vcc, 0, v115, vcc
	global_store_dwordx2 v[2:3], v[6:7], off nt
	v_add_co_u32_e32 v2, vcc, 0x2c3000, v114
	s_nop 1
	v_addc_co_u32_e32 v3, vcc, 0, v115, vcc
	global_store_dwordx2 v[2:3], v[14:15], off nt
	s_and_b64 vcc, exec, s[40:41]
	s_mov_b64 s[40:41], -1
	s_cbranch_vccnz .LBB0_226
